# final f32 output stores of the layer-1 epilogues marked non-temporal (streaming)
# speedup vs baseline: 1.0030x; 1.0030x over previous
; DI float bf2f(unsigned b) { return __uint_as_float(b << 16); }
; DI void unit_O(const Params& p, char* lds, int l, int tile, int glu_tiles, int tile_b) {
;     ...
; #pragma unroll 1
;             for (int i = 0; i < 8; ++i) {
;                 const int pc = (wid * 8 + i + (xrot >> 1)) & 63, kt = pc >> 1, sub = pc & 1;
;                 __builtin_amdgcn_global_load_lds((const unsigned*)(xbres + ((size_t)kt * 128 + half * 32) * 32 + sub * 512 + lane * 8), (unsigned*)(XR + pc * 1024 + lane * 16), 16, 0, 0);
;             }
;     ...
;         float s2[2], ss2[2];
; #pragma unroll
;         for (int mh = 0; mh < 2; ++mh) {
;             const int mt = half * 2 + mh, rl = mh * 16 + l15;
;             float s = 0.f, ss = 0.f;
; #pragma unroll
;             for (int nt = 0; nt < 8; ++nt) {
;                 f32x4 xr;
;                 if (l == 0) {
;                     const int chunk = wid * 32 + nt * 4 + quad;
;                     xr = *(const f32x4*)(XR + rl * 4096 + ((chunk ^ l15) << 4));
;                 } else {
;                     const u32x2 hb = *(const u32x2*)(XR + ((wid * 4 + (nt >> 1)) * 32 + rl) * 64 + (nt & 1) * 32 + quad * 8);
;                     xr = (f32x4){bf2f(hb[0] & 0xffffu), bf2f(hb[0] >> 16), bf2f(hb[1] & 0xffffu), bf2f(hb[1] >> 16)};
;                 }
; #pragma unroll
;                 for (int i = 0; i < 4; ++i) { const float v = acc[mt][nt][i] + DN_ALPHA * xr[i]; acc[mt][nt][i] = v; s += v; ss += v * v; }
;             }
;             s2[mh] = s; ss2[mh] = ss;
;         }
; #pragma unroll
;         for (int mh = 0; mh < 2; ++mh) { s2[mh] += __shfl_xor(s2[mh], 16); ss2[mh] += __shfl_xor(ss2[mh], 16); }
; #pragma unroll
;         for (int mh = 0; mh < 2; ++mh) { s2[mh] += __shfl_xor(s2[mh], 32); ss2[mh] += __shfl_xor(ss2[mh], 32); }
;         if (quad == 0) {
; #pragma unroll
;             for (int mh = 0; mh < 2; ++mh) *(f32x2*)&red[((mh * 16 + l15) * 8 + wid) * 2] = (f32x2){s2[mh], ss2[mh]};
;         }
;         __syncthreads();
.Le1_l1:
	s_lshr_b32 s40, s34, 1
	s_lshl_b32 s40, s40, 18
	s_and_b32 s94, s34, 1
	s_lshl_b32 s94, s94, 12
	s_add_u32 s40, s40, s94
	s_lshl_b32 s91, s90, 12
	s_lshl_b32 s94, s90, 15
	s_add_u32 s96, s56, s40
	s_addc_u32 s97, s57, 0
	s_add_u32 s96, s96, s94
	s_addc_u32 s97, s97, 0
	v_lshlrev_b32_e32 v208, 4, v141
	v_lshlrev_b32_e32 v133, 12, v140
	v_lshl_add_u32 v133, v138, 6, v133
	v_lshl_add_u32 v133, v139, 3, v133
	v_lshlrev_b32_e32 v137, 12, v138
	v_lshl_add_u32 v137, v140, 9, v137
	v_lshl_add_u32 v137, v139, 4, v137
	s_lshl_b32 s40, s34, 18
	s_add_u32 s78, s16, s40
	s_addc_u32 s79, s17, 0
	s_add_u32 s92, s96, 0x0
	s_addc_u32 s93, s97, 0
	s_add_u32 s40, s91, 0x0
	s_mov_b32 m0, s40
	s_nop 0
	global_load_lds_dwordx4 v208, s[92:93]
	s_add_u32 s92, s92, 0x2000
	s_addc_u32 s93, s93, 0
	s_add_u32 m0, m0, 0x400
	s_nop 0
	global_load_lds_dwordx4 v208, s[92:93]
	s_add_u32 s92, s92, 0x2000
	s_addc_u32 s93, s93, 0
	s_add_u32 m0, m0, 0x400
	s_nop 0
	global_load_lds_dwordx4 v208, s[92:93]
	s_add_u32 s92, s92, 0x2000
	s_addc_u32 s93, s93, 0
	s_add_u32 m0, m0, 0x400
	s_nop 0
	global_load_lds_dwordx4 v208, s[92:93]
	s_add_u32 s92, s96, 0x400
	s_addc_u32 s93, s97, 0
	s_add_u32 s40, s91, 0x8000
	s_mov_b32 m0, s40
	s_nop 0
	global_load_lds_dwordx4 v208, s[92:93]
	s_add_u32 s92, s92, 0x2000
	s_addc_u32 s93, s93, 0
	s_add_u32 m0, m0, 0x400
	s_nop 0
	global_load_lds_dwordx4 v208, s[92:93]
	s_add_u32 s92, s92, 0x2000
	s_addc_u32 s93, s93, 0
	s_add_u32 m0, m0, 0x400
	s_nop 0
	global_load_lds_dwordx4 v208, s[92:93]
	s_add_u32 s92, s92, 0x2000
	s_addc_u32 s93, s93, 0
	s_add_u32 m0, m0, 0x400
	s_nop 0
	global_load_lds_dwordx4 v208, s[92:93]
	s_waitcnt vmcnt(8)
	ds_write_b128 v143, v[176:179]
	s_waitcnt vmcnt(4) lgkmcnt(0)
	s_barrier
	ds_read_b64 v[180:181], v133 offset:0
	ds_read_b64 v[182:183], v133 offset:32
	ds_read_b64 v[184:185], v133 offset:1024
	ds_read_b64 v[186:187], v133 offset:1056
	ds_read_b64 v[188:189], v133 offset:2048
	ds_read_b64 v[190:191], v133 offset:2080
	ds_read_b64 v[192:193], v133 offset:3072
	ds_read_b64 v[194:195], v133 offset:3104
	s_waitcnt lgkmcnt(7)
	v_lshlrev_b32_e32 v144, 16, v180
	v_and_b32_e32 v145, 0xffff0000, v180
	v_lshlrev_b32_e32 v146, 16, v181
	v_and_b32_e32 v147, 0xffff0000, v181
	v_fmac_f32_e32 v98, s58, v144
	v_fmac_f32_e32 v99, s58, v145
	v_fmac_f32_e32 v100, s58, v146
	v_fmac_f32_e32 v101, s58, v147
	v_mov_b32_e32 v196, v98
	v_mul_f32_e32 v197, v98, v98
	v_mov_b32_e32 v130, v99
	v_mul_f32_e32 v142, v99, v99
	v_add_f32_e32 v196, v196, v100
	v_fmac_f32_e32 v197, v100, v100
	v_add_f32_e32 v130, v130, v101
	v_fmac_f32_e32 v142, v101, v101
	s_waitcnt lgkmcnt(6)
	v_lshlrev_b32_e32 v148, 16, v182
	v_and_b32_e32 v149, 0xffff0000, v182
	v_lshlrev_b32_e32 v150, 16, v183
	v_and_b32_e32 v151, 0xffff0000, v183
	v_fmac_f32_e32 v94, s58, v148
	v_fmac_f32_e32 v95, s58, v149
	v_fmac_f32_e32 v96, s58, v150
	v_fmac_f32_e32 v97, s58, v151
	v_add_f32_e32 v196, v196, v94
	v_fmac_f32_e32 v197, v94, v94
	v_add_f32_e32 v130, v130, v95
	v_fmac_f32_e32 v142, v95, v95
	v_add_f32_e32 v196, v196, v96
	v_fmac_f32_e32 v197, v96, v96
	v_add_f32_e32 v130, v130, v97
	v_fmac_f32_e32 v142, v97, v97
	s_waitcnt lgkmcnt(5)
	v_lshlrev_b32_e32 v152, 16, v184
	v_and_b32_e32 v153, 0xffff0000, v184
	v_lshlrev_b32_e32 v154, 16, v185
	v_and_b32_e32 v155, 0xffff0000, v185
	v_fmac_f32_e32 v90, s58, v152
	v_fmac_f32_e32 v91, s58, v153
	v_fmac_f32_e32 v92, s58, v154
	v_fmac_f32_e32 v93, s58, v155
	v_add_f32_e32 v196, v196, v90
	v_fmac_f32_e32 v197, v90, v90
	v_add_f32_e32 v130, v130, v91
	v_fmac_f32_e32 v142, v91, v91
	v_add_f32_e32 v196, v196, v92
	v_fmac_f32_e32 v197, v92, v92
	v_add_f32_e32 v130, v130, v93
	v_fmac_f32_e32 v142, v93, v93
	s_waitcnt lgkmcnt(4)
	v_lshlrev_b32_e32 v156, 16, v186
	v_and_b32_e32 v157, 0xffff0000, v186
	v_lshlrev_b32_e32 v158, 16, v187
	v_and_b32_e32 v159, 0xffff0000, v187
	v_fmac_f32_e32 v86, s58, v156
	v_fmac_f32_e32 v87, s58, v157
	v_fmac_f32_e32 v88, s58, v158
	v_fmac_f32_e32 v89, s58, v159
	v_add_f32_e32 v196, v196, v86
	v_fmac_f32_e32 v197, v86, v86
	v_add_f32_e32 v130, v130, v87
	v_fmac_f32_e32 v142, v87, v87
	v_add_f32_e32 v196, v196, v88
	v_fmac_f32_e32 v197, v88, v88
	v_add_f32_e32 v130, v130, v89
	v_fmac_f32_e32 v142, v89, v89
	s_waitcnt lgkmcnt(3)
	v_lshlrev_b32_e32 v160, 16, v188
	v_and_b32_e32 v161, 0xffff0000, v188
	v_lshlrev_b32_e32 v162, 16, v189
	v_and_b32_e32 v163, 0xffff0000, v189
	v_fmac_f32_e32 v82, s58, v160
	v_fmac_f32_e32 v83, s58, v161
	v_fmac_f32_e32 v84, s58, v162
	v_fmac_f32_e32 v85, s58, v163
	v_add_f32_e32 v196, v196, v82
	v_fmac_f32_e32 v197, v82, v82
	v_add_f32_e32 v130, v130, v83
	v_fmac_f32_e32 v142, v83, v83
	v_add_f32_e32 v196, v196, v84
	v_fmac_f32_e32 v197, v84, v84
	v_add_f32_e32 v130, v130, v85
	v_fmac_f32_e32 v142, v85, v85
	s_waitcnt lgkmcnt(2)
	v_lshlrev_b32_e32 v164, 16, v190
	v_and_b32_e32 v165, 0xffff0000, v190
	v_lshlrev_b32_e32 v166, 16, v191
	v_and_b32_e32 v167, 0xffff0000, v191
	v_fmac_f32_e32 v78, s58, v164
	v_fmac_f32_e32 v79, s58, v165
	v_fmac_f32_e32 v80, s58, v166
	v_fmac_f32_e32 v81, s58, v167
	v_add_f32_e32 v196, v196, v78
	v_fmac_f32_e32 v197, v78, v78
	v_add_f32_e32 v130, v130, v79
	v_fmac_f32_e32 v142, v79, v79
	v_add_f32_e32 v196, v196, v80
	v_fmac_f32_e32 v197, v80, v80
	v_add_f32_e32 v130, v130, v81
	v_fmac_f32_e32 v142, v81, v81
	s_waitcnt lgkmcnt(1)
	v_lshlrev_b32_e32 v168, 16, v192
	v_and_b32_e32 v169, 0xffff0000, v192
	v_lshlrev_b32_e32 v170, 16, v193
	v_and_b32_e32 v171, 0xffff0000, v193
	v_fmac_f32_e32 v74, s58, v168
	v_fmac_f32_e32 v75, s58, v169
	v_fmac_f32_e32 v76, s58, v170
	v_fmac_f32_e32 v77, s58, v171
	v_add_f32_e32 v196, v196, v74
	v_fmac_f32_e32 v197, v74, v74
	v_add_f32_e32 v130, v130, v75
	v_fmac_f32_e32 v142, v75, v75
	v_add_f32_e32 v196, v196, v76
	v_fmac_f32_e32 v197, v76, v76
	v_add_f32_e32 v130, v130, v77
	v_fmac_f32_e32 v142, v77, v77
	s_waitcnt lgkmcnt(0)
	v_lshlrev_b32_e32 v172, 16, v194
	v_and_b32_e32 v173, 0xffff0000, v194
	v_lshlrev_b32_e32 v174, 16, v195
	v_and_b32_e32 v175, 0xffff0000, v195
	v_fmac_f32_e32 v70, s58, v172
	v_fmac_f32_e32 v71, s58, v173
	v_fmac_f32_e32 v72, s58, v174
	v_fmac_f32_e32 v73, s58, v175
	v_add_f32_e32 v196, v196, v70
	v_fmac_f32_e32 v197, v70, v70
	v_add_f32_e32 v130, v130, v71
	v_fmac_f32_e32 v142, v71, v71
	v_add_f32_e32 v196, v196, v72
	v_fmac_f32_e32 v197, v72, v72
	v_add_f32_e32 v130, v130, v73
	v_fmac_f32_e32 v142, v73, v73
	v_add_f32_e32 v196, v196, v130
	v_add_f32_e32 v197, v197, v142
	v_mov_b32_e32 v198, v196
	v_mov_b32_e32 v199, v197
	s_nop 1
	v_permlane16_swap_b32 v198, v196
	v_permlane16_swap_b32 v199, v197
	v_add_f32_e32 v196, v196, v198
	v_add_f32_e32 v197, v197, v199
	v_mov_b32_e32 v198, v196
	v_mov_b32_e32 v199, v197
	s_nop 1
	v_permlane32_swap_b32 v198, v196
	v_permlane32_swap_b32 v199, v197
	v_add_f32_e32 v196, v196, v198
	v_add_f32_e32 v197, v197, v199
	s_mov_b64 exec, 0xffff
	ds_write_b64 v134, v[196:197]
	s_mov_b64 exec, -1
	s_waitcnt lgkmcnt(0)
	s_barrier
; DI unsigned pk2(float lo, float hi) { const f32x2 v = {lo, hi}; const bf16x2_t b = __builtin_convertvector(v, bf16x2_t); return __builtin_bit_cast(unsigned, b); }
; DI size_t xb_off(int tok, int col) { return ((size_t)(((tok >> 7) * 32 + (col >> 5)) * 128 + (tok & 127))) * 32 + (col & 31); }
; DI void unit_O(const Params& p, char* lds, int l, int tile, int glu_tiles, int tile_b) {
;     ...
; #pragma unroll 1
;             for (int i = 0; i < 8; ++i) {
;                 const int pc = (wid * 8 + i + (xrot >> 1)) & 63, kt = pc >> 1, sub = pc & 1;
;                 __builtin_amdgcn_global_load_lds((const unsigned*)(xbres + ((size_t)kt * 128 + half * 32) * 32 + sub * 512 + lane * 8), (unsigned*)(XR + pc * 1024 + lane * 16), 16, 0, 0);
;             }
;     ...
; #pragma unroll
;         for (int mh = 0; mh < 2; ++mh) {
;             const int mt = half * 2 + mh, rl = mh * 16 + l15, row = mt * 16 + l15;
;             float s = 0.f, ss = 0.f;
; #pragma unroll
;             for (int w = 0; w < 4; ++w) { const f32x4 v = *(const f32x4*)&red[rl * 16 + 4 * w]; s += v[0] + v[2]; ss += v[1] + v[3]; }
;             const float mu = s * (1.f / 1024.f);
;             const float var = ss * (1.f / 1024.f) - mu * mu;
;             const float rs = rsqrtf(var + LN_EPS);
;             float* orow = xo + (r0 + row) * 1024 + wid * 128 + quad * 4;
;             bf16_t* brow = xbo + xb_off((int)r0 + row, wid * 128) + quad * 4;
;             const float* gp = GB + wid * 128 + quad * 4;
; #pragma unroll
;             for (int nt = 0; nt < 8; ++nt) {
;                 const f32x4 g = *(const f32x4*)(gp + nt * 16), bb = *(const f32x4*)(gp + 1024 + nt * 16);
;                 f32x4 o;
; #pragma unroll
;                 for (int i = 0; i < 4; ++i) o[i] = (acc[mt][nt][i] - mu) * rs * g[i] + bb[i];
;                 if (l == 0) *(u32x2*)(brow + (nt >> 1) * 4096 + (nt & 1) * 16) = (u32x2){pk2(o[0], o[1]), pk2(o[2], o[3])};
;                 else *(f32x4*)(orow + nt * 16) = o;
;             }
	s_add_u32 s92, s96, 0x800
	s_addc_u32 s93, s97, 0
	s_add_u32 s40, s91, 0x0
	s_mov_b32 m0, s40
	s_nop 0
	global_load_lds_dwordx4 v208, s[92:93]
	s_add_u32 s92, s92, 0x2000
	s_addc_u32 s93, s93, 0
	s_add_u32 m0, m0, 0x400
	s_nop 0
	global_load_lds_dwordx4 v208, s[92:93]
	s_add_u32 s92, s92, 0x2000
	s_addc_u32 s93, s93, 0
	s_add_u32 m0, m0, 0x400
	s_nop 0
	global_load_lds_dwordx4 v208, s[92:93]
	s_add_u32 s92, s92, 0x2000
	s_addc_u32 s93, s93, 0
	s_add_u32 m0, m0, 0x400
	s_nop 0
	global_load_lds_dwordx4 v208, s[92:93]
	ds_read_b128 v[160:163], v135 offset:0
	ds_read_b128 v[164:167], v135 offset:16
	ds_read_b128 v[168:171], v135 offset:32
	ds_read_b128 v[172:175], v135 offset:48
	s_waitcnt lgkmcnt(0)
	v_add_f32_e32 v160, v160, v162
	v_add_f32_e32 v161, v161, v163
	v_add_f32_e32 v164, v164, v166
	v_add_f32_e32 v165, v165, v167
	v_add_f32_e32 v168, v168, v170
	v_add_f32_e32 v169, v169, v171
	v_add_f32_e32 v172, v172, v174
	v_add_f32_e32 v173, v173, v175
	v_add_f32_e32 v160, v160, v164
	v_add_f32_e32 v161, v161, v165
	v_add_f32_e32 v168, v168, v172
	v_add_f32_e32 v169, v169, v173
	v_add_f32_e32 v160, v160, v168
	v_add_f32_e32 v161, v161, v169
	v_mul_f32_e32 v192, 0x3a800000, v160
	v_mul_f32_e32 v193, 0x3a800000, v161
	v_fma_f32 v193, -v192, v192, v193
	v_add_f32_e32 v193, 0x3727c5ac, v193
	v_rsq_f32_e32 v193, v193
	s_nop 0
	s_add_u32 s94, s78, 0x0
	s_addc_u32 s95, s79, 0
	ds_read_b128 v[176:179], v136
	ds_read_b128 v[180:183], v136 offset:4096
	ds_read_b128 v[184:187], v136 offset:64
	ds_read_b128 v[188:191], v136 offset:4160
	s_waitcnt lgkmcnt(2)
	v_sub_f32_e32 v98, v98, v192
	v_mul_f32_e32 v98, v98, v193
	v_fma_f32 v98, v176, v98, v180
	v_sub_f32_e32 v99, v99, v192
	v_mul_f32_e32 v99, v99, v193
	v_fma_f32 v99, v177, v99, v181
	v_sub_f32_e32 v100, v100, v192
	v_mul_f32_e32 v100, v100, v193
	v_fma_f32 v100, v178, v100, v182
	v_sub_f32_e32 v101, v101, v192
	v_mul_f32_e32 v101, v101, v193
	v_fma_f32 v101, v179, v101, v183
	global_store_dwordx4 v137, v[98:101], s[94:95] nt
	ds_read_b128 v[176:179], v136 offset:128
	ds_read_b128 v[180:183], v136 offset:4224
	s_waitcnt lgkmcnt(2)
	v_sub_f32_e32 v94, v94, v192
	v_mul_f32_e32 v94, v94, v193
	v_fma_f32 v94, v184, v94, v188
	v_sub_f32_e32 v95, v95, v192
	v_mul_f32_e32 v95, v95, v193
	v_fma_f32 v95, v185, v95, v189
	v_sub_f32_e32 v96, v96, v192
	v_mul_f32_e32 v96, v96, v193
	v_fma_f32 v96, v186, v96, v190
	v_sub_f32_e32 v97, v97, v192
	v_mul_f32_e32 v97, v97, v193
	v_fma_f32 v97, v187, v97, v191
	global_store_dwordx4 v137, v[94:97], s[94:95] offset:64 nt
	ds_read_b128 v[184:187], v136 offset:192
	ds_read_b128 v[188:191], v136 offset:4288
	s_waitcnt lgkmcnt(2)
	v_sub_f32_e32 v90, v90, v192
	v_mul_f32_e32 v90, v90, v193
	v_fma_f32 v90, v176, v90, v180
	v_sub_f32_e32 v91, v91, v192
	v_mul_f32_e32 v91, v91, v193
	v_fma_f32 v91, v177, v91, v181
	v_sub_f32_e32 v92, v92, v192
	v_mul_f32_e32 v92, v92, v193
	v_fma_f32 v92, v178, v92, v182
	v_sub_f32_e32 v93, v93, v192
	v_mul_f32_e32 v93, v93, v193
	v_fma_f32 v93, v179, v93, v183
	global_store_dwordx4 v137, v[90:93], s[94:95] offset:128 nt
	ds_read_b128 v[176:179], v136 offset:256
	ds_read_b128 v[180:183], v136 offset:4352
	s_waitcnt lgkmcnt(2)
	v_sub_f32_e32 v86, v86, v192
	v_mul_f32_e32 v86, v86, v193
	v_fma_f32 v86, v184, v86, v188
	v_sub_f32_e32 v87, v87, v192
	v_mul_f32_e32 v87, v87, v193
	v_fma_f32 v87, v185, v87, v189
	v_sub_f32_e32 v88, v88, v192
	v_mul_f32_e32 v88, v88, v193
	v_fma_f32 v88, v186, v88, v190
	v_sub_f32_e32 v89, v89, v192
	v_mul_f32_e32 v89, v89, v193
	v_fma_f32 v89, v187, v89, v191
	global_store_dwordx4 v137, v[86:89], s[94:95] offset:192 nt
	ds_read_b128 v[184:187], v136 offset:320
	ds_read_b128 v[188:191], v136 offset:4416
	s_waitcnt lgkmcnt(2)
	v_sub_f32_e32 v82, v82, v192
	v_mul_f32_e32 v82, v82, v193
	v_fma_f32 v82, v176, v82, v180
	v_sub_f32_e32 v83, v83, v192
	v_mul_f32_e32 v83, v83, v193
	v_fma_f32 v83, v177, v83, v181
	v_sub_f32_e32 v84, v84, v192
	v_mul_f32_e32 v84, v84, v193
	v_fma_f32 v84, v178, v84, v182
	v_sub_f32_e32 v85, v85, v192
	v_mul_f32_e32 v85, v85, v193
	v_fma_f32 v85, v179, v85, v183
	global_store_dwordx4 v137, v[82:85], s[94:95] offset:256 nt
	ds_read_b128 v[176:179], v136 offset:384
	ds_read_b128 v[180:183], v136 offset:4480
	s_waitcnt lgkmcnt(2)
	v_sub_f32_e32 v78, v78, v192
	v_mul_f32_e32 v78, v78, v193
	v_fma_f32 v78, v184, v78, v188
	v_sub_f32_e32 v79, v79, v192
	v_mul_f32_e32 v79, v79, v193
	v_fma_f32 v79, v185, v79, v189
	v_sub_f32_e32 v80, v80, v192
	v_mul_f32_e32 v80, v80, v193
	v_fma_f32 v80, v186, v80, v190
	v_sub_f32_e32 v81, v81, v192
	v_mul_f32_e32 v81, v81, v193
	v_fma_f32 v81, v187, v81, v191
	global_store_dwordx4 v137, v[78:81], s[94:95] offset:320 nt
	ds_read_b128 v[184:187], v136 offset:448
	ds_read_b128 v[188:191], v136 offset:4544
	s_waitcnt lgkmcnt(2)
	v_sub_f32_e32 v74, v74, v192
	v_mul_f32_e32 v74, v74, v193
	v_fma_f32 v74, v176, v74, v180
	v_sub_f32_e32 v75, v75, v192
	v_mul_f32_e32 v75, v75, v193
	v_fma_f32 v75, v177, v75, v181
	v_sub_f32_e32 v76, v76, v192
	v_mul_f32_e32 v76, v76, v193
	v_fma_f32 v76, v178, v76, v182
	v_sub_f32_e32 v77, v77, v192
	v_mul_f32_e32 v77, v77, v193
	v_fma_f32 v77, v179, v77, v183
	global_store_dwordx4 v137, v[74:77], s[94:95] offset:384 nt
	s_waitcnt lgkmcnt(0)
	v_sub_f32_e32 v70, v70, v192
	v_mul_f32_e32 v70, v70, v193
	v_fma_f32 v70, v184, v70, v188
	v_sub_f32_e32 v71, v71, v192
	v_mul_f32_e32 v71, v71, v193
	v_fma_f32 v71, v185, v71, v189
	v_sub_f32_e32 v72, v72, v192
	v_mul_f32_e32 v72, v72, v193
	v_fma_f32 v72, v186, v72, v190
	v_sub_f32_e32 v73, v73, v192
	v_mul_f32_e32 v73, v73, v193
	v_fma_f32 v73, v187, v73, v191
	global_store_dwordx4 v137, v[70:73], s[94:95] offset:448 nt
	s_waitcnt vmcnt(12) lgkmcnt(0)
	s_barrier
; DI float bf2f(unsigned b) { return __uint_as_float(b << 16); }
; DI void unit_O(const Params& p, char* lds, int l, int tile, int glu_tiles, int tile_b) {
;     ...
;         float s2[2], ss2[2];
; #pragma unroll
;         for (int mh = 0; mh < 2; ++mh) {
;             const int mt = half * 2 + mh, rl = mh * 16 + l15;
;             float s = 0.f, ss = 0.f;
; #pragma unroll
;             for (int nt = 0; nt < 8; ++nt) {
;                 f32x4 xr;
;                 if (l == 0) {
;                     const int chunk = wid * 32 + nt * 4 + quad;
;                     xr = *(const f32x4*)(XR + rl * 4096 + ((chunk ^ l15) << 4));
;                 } else {
;                     const u32x2 hb = *(const u32x2*)(XR + ((wid * 4 + (nt >> 1)) * 32 + rl) * 64 + (nt & 1) * 32 + quad * 8);
;                     xr = (f32x4){bf2f(hb[0] & 0xffffu), bf2f(hb[0] >> 16), bf2f(hb[1] & 0xffffu), bf2f(hb[1] >> 16)};
;                 }
; #pragma unroll
;                 for (int i = 0; i < 4; ++i) { const float v = acc[mt][nt][i] + DN_ALPHA * xr[i]; acc[mt][nt][i] = v; s += v; ss += v * v; }
;             }
;             s2[mh] = s; ss2[mh] = ss;
;         }
; #pragma unroll
;         for (int mh = 0; mh < 2; ++mh) { s2[mh] += __shfl_xor(s2[mh], 16); ss2[mh] += __shfl_xor(ss2[mh], 16); }
; #pragma unroll
;         for (int mh = 0; mh < 2; ++mh) { s2[mh] += __shfl_xor(s2[mh], 32); ss2[mh] += __shfl_xor(ss2[mh], 32); }
;         if (quad == 0) {
; #pragma unroll
;             for (int mh = 0; mh < 2; ++mh) *(f32x2*)&red[((mh * 16 + l15) * 8 + wid) * 2] = (f32x2){s2[mh], ss2[mh]};
;         }
;         __syncthreads();
	ds_read_b64 v[180:181], v133 offset:32768
	ds_read_b64 v[182:183], v133 offset:32800
	ds_read_b64 v[184:185], v133 offset:33792
	ds_read_b64 v[186:187], v133 offset:33824
	ds_read_b64 v[188:189], v133 offset:34816
	ds_read_b64 v[190:191], v133 offset:34848
	ds_read_b64 v[192:193], v133 offset:35840
	ds_read_b64 v[194:195], v133 offset:35872
	s_waitcnt lgkmcnt(7)
	v_lshlrev_b32_e32 v144, 16, v180
	v_and_b32_e32 v145, 0xffff0000, v180
	v_lshlrev_b32_e32 v146, 16, v181
	v_and_b32_e32 v147, 0xffff0000, v181
	v_fmac_f32_e32 v126, s58, v144
	v_fmac_f32_e32 v127, s58, v145
	v_fmac_f32_e32 v128, s58, v146
	v_fmac_f32_e32 v129, s58, v147
	v_mov_b32_e32 v196, v126
	v_mul_f32_e32 v197, v126, v126
	v_mov_b32_e32 v130, v127
	v_mul_f32_e32 v142, v127, v127
	v_add_f32_e32 v196, v196, v128
	v_fmac_f32_e32 v197, v128, v128
	v_add_f32_e32 v130, v130, v129
	v_fmac_f32_e32 v142, v129, v129
	s_waitcnt lgkmcnt(6)
	v_lshlrev_b32_e32 v148, 16, v182
	v_and_b32_e32 v149, 0xffff0000, v182
	v_lshlrev_b32_e32 v150, 16, v183
	v_and_b32_e32 v151, 0xffff0000, v183
	v_fmac_f32_e32 v122, s58, v148
	v_fmac_f32_e32 v123, s58, v149
	v_fmac_f32_e32 v124, s58, v150
	v_fmac_f32_e32 v125, s58, v151
	v_add_f32_e32 v196, v196, v122
	v_fmac_f32_e32 v197, v122, v122
	v_add_f32_e32 v130, v130, v123
	v_fmac_f32_e32 v142, v123, v123
	v_add_f32_e32 v196, v196, v124
	v_fmac_f32_e32 v197, v124, v124
	v_add_f32_e32 v130, v130, v125
	v_fmac_f32_e32 v142, v125, v125
	s_waitcnt lgkmcnt(5)
	v_lshlrev_b32_e32 v152, 16, v184
	v_and_b32_e32 v153, 0xffff0000, v184
	v_lshlrev_b32_e32 v154, 16, v185
	v_and_b32_e32 v155, 0xffff0000, v185
	v_fmac_f32_e32 v118, s58, v152
	v_fmac_f32_e32 v119, s58, v153
	v_fmac_f32_e32 v120, s58, v154
	v_fmac_f32_e32 v121, s58, v155
	v_add_f32_e32 v196, v196, v118
	v_fmac_f32_e32 v197, v118, v118
	v_add_f32_e32 v130, v130, v119
	v_fmac_f32_e32 v142, v119, v119
	v_add_f32_e32 v196, v196, v120
	v_fmac_f32_e32 v197, v120, v120
	v_add_f32_e32 v130, v130, v121
	v_fmac_f32_e32 v142, v121, v121
	s_waitcnt lgkmcnt(4)
	v_lshlrev_b32_e32 v156, 16, v186
	v_and_b32_e32 v157, 0xffff0000, v186
	v_lshlrev_b32_e32 v158, 16, v187
	v_and_b32_e32 v159, 0xffff0000, v187
	v_fmac_f32_e32 v114, s58, v156
	v_fmac_f32_e32 v115, s58, v157
	v_fmac_f32_e32 v116, s58, v158
	v_fmac_f32_e32 v117, s58, v159
	v_add_f32_e32 v196, v196, v114
	v_fmac_f32_e32 v197, v114, v114
	v_add_f32_e32 v130, v130, v115
	v_fmac_f32_e32 v142, v115, v115
	v_add_f32_e32 v196, v196, v116
	v_fmac_f32_e32 v197, v116, v116
	v_add_f32_e32 v130, v130, v117
	v_fmac_f32_e32 v142, v117, v117
	s_waitcnt lgkmcnt(3)
	v_lshlrev_b32_e32 v160, 16, v188
	v_and_b32_e32 v161, 0xffff0000, v188
	v_lshlrev_b32_e32 v162, 16, v189
	v_and_b32_e32 v163, 0xffff0000, v189
	v_fmac_f32_e32 v110, s58, v160
	v_fmac_f32_e32 v111, s58, v161
	v_fmac_f32_e32 v112, s58, v162
	v_fmac_f32_e32 v113, s58, v163
	v_add_f32_e32 v196, v196, v110
	v_fmac_f32_e32 v197, v110, v110
	v_add_f32_e32 v130, v130, v111
	v_fmac_f32_e32 v142, v111, v111
	v_add_f32_e32 v196, v196, v112
	v_fmac_f32_e32 v197, v112, v112
	v_add_f32_e32 v130, v130, v113
	v_fmac_f32_e32 v142, v113, v113
	s_waitcnt lgkmcnt(2)
	v_lshlrev_b32_e32 v164, 16, v190
	v_and_b32_e32 v165, 0xffff0000, v190
	v_lshlrev_b32_e32 v166, 16, v191
	v_and_b32_e32 v167, 0xffff0000, v191
	v_fmac_f32_e32 v106, s58, v164
	v_fmac_f32_e32 v107, s58, v165
	v_fmac_f32_e32 v108, s58, v166
	v_fmac_f32_e32 v109, s58, v167
	v_add_f32_e32 v196, v196, v106
	v_fmac_f32_e32 v197, v106, v106
	v_add_f32_e32 v130, v130, v107
	v_fmac_f32_e32 v142, v107, v107
	v_add_f32_e32 v196, v196, v108
	v_fmac_f32_e32 v197, v108, v108
	v_add_f32_e32 v130, v130, v109
	v_fmac_f32_e32 v142, v109, v109
	s_waitcnt lgkmcnt(1)
	v_lshlrev_b32_e32 v168, 16, v192
	v_and_b32_e32 v169, 0xffff0000, v192
	v_lshlrev_b32_e32 v170, 16, v193
	v_and_b32_e32 v171, 0xffff0000, v193
	v_fmac_f32_e32 v102, s58, v168
	v_fmac_f32_e32 v103, s58, v169
	v_fmac_f32_e32 v104, s58, v170
	v_fmac_f32_e32 v105, s58, v171
	v_add_f32_e32 v196, v196, v102
	v_fmac_f32_e32 v197, v102, v102
	v_add_f32_e32 v130, v130, v103
	v_fmac_f32_e32 v142, v103, v103
	v_add_f32_e32 v196, v196, v104
	v_fmac_f32_e32 v197, v104, v104
	v_add_f32_e32 v130, v130, v105
	v_fmac_f32_e32 v142, v105, v105
	s_waitcnt lgkmcnt(0)
	v_lshlrev_b32_e32 v172, 16, v194
	v_and_b32_e32 v173, 0xffff0000, v194
	v_lshlrev_b32_e32 v174, 16, v195
	v_and_b32_e32 v175, 0xffff0000, v195
	v_fmac_f32_e32 v66, s58, v172
	v_fmac_f32_e32 v67, s58, v173
	v_fmac_f32_e32 v68, s58, v174
	v_fmac_f32_e32 v69, s58, v175
	v_add_f32_e32 v196, v196, v66
	v_fmac_f32_e32 v197, v66, v66
	v_add_f32_e32 v130, v130, v67
	v_fmac_f32_e32 v142, v67, v67
	v_add_f32_e32 v196, v196, v68
	v_fmac_f32_e32 v197, v68, v68
	v_add_f32_e32 v130, v130, v69
	v_fmac_f32_e32 v142, v69, v69
	v_add_f32_e32 v196, v196, v130
	v_add_f32_e32 v197, v197, v142
	v_mov_b32_e32 v198, v196
	v_mov_b32_e32 v199, v197
	s_nop 1
	v_permlane16_swap_b32 v198, v196
	v_permlane16_swap_b32 v199, v197
	v_add_f32_e32 v196, v196, v198
	v_add_f32_e32 v197, v197, v199
	v_mov_b32_e32 v198, v196
	v_mov_b32_e32 v199, v197
	s_nop 1
	v_permlane32_swap_b32 v198, v196
	v_permlane32_swap_b32 v199, v197
	v_add_f32_e32 v196, v196, v198
	v_add_f32_e32 v197, v197, v199
	s_mov_b64 exec, 0xffff
	ds_write_b64 v134, v[196:197]
	s_mov_b64 exec, -1
	s_waitcnt lgkmcnt(0)
	s_barrier
; DI unsigned pk2(float lo, float hi) { const f32x2 v = {lo, hi}; const bf16x2_t b = __builtin_convertvector(v, bf16x2_t); return __builtin_bit_cast(unsigned, b); }
; DI size_t xb_off(int tok, int col) { return ((size_t)(((tok >> 7) * 32 + (col >> 5)) * 128 + (tok & 127))) * 32 + (col & 31); }
; DI void unit_O(const Params& p, char* lds, int l, int tile, int glu_tiles, int tile_b) {
;     ...
; #pragma unroll 1
;             for (int i = 0; i < 8; ++i) {
;                 const int pc = (wid * 8 + i + (xrot >> 1)) & 63, kt = pc >> 1, sub = pc & 1;
;                 __builtin_amdgcn_global_load_lds((const unsigned*)(xbres + ((size_t)kt * 128 + half * 32) * 32 + sub * 512 + lane * 8), (unsigned*)(XR + pc * 1024 + lane * 16), 16, 0, 0);
;             }
;     ...
; #pragma unroll
;         for (int mh = 0; mh < 2; ++mh) {
;             const int mt = half * 2 + mh, rl = mh * 16 + l15, row = mt * 16 + l15;
;             float s = 0.f, ss = 0.f;
; #pragma unroll
;             for (int w = 0; w < 4; ++w) { const f32x4 v = *(const f32x4*)&red[rl * 16 + 4 * w]; s += v[0] + v[2]; ss += v[1] + v[3]; }
;             const float mu = s * (1.f / 1024.f);
;             const float var = ss * (1.f / 1024.f) - mu * mu;
;             const float rs = rsqrtf(var + LN_EPS);
;             float* orow = xo + (r0 + row) * 1024 + wid * 128 + quad * 4;
;             bf16_t* brow = xbo + xb_off((int)r0 + row, wid * 128) + quad * 4;
;             const float* gp = GB + wid * 128 + quad * 4;
; #pragma unroll
;             for (int nt = 0; nt < 8; ++nt) {
;                 const f32x4 g = *(const f32x4*)(gp + nt * 16), bb = *(const f32x4*)(gp + 1024 + nt * 16);
;                 f32x4 o;
; #pragma unroll
;                 for (int i = 0; i < 4; ++i) o[i] = (acc[mt][nt][i] - mu) * rs * g[i] + bb[i];
;                 if (l == 0) *(u32x2*)(brow + (nt >> 1) * 4096 + (nt & 1) * 16) = (u32x2){pk2(o[0], o[1]), pk2(o[2], o[3])};
;                 else *(f32x4*)(orow + nt * 16) = o;
;             }
	s_add_u32 s92, s96, 0xc00
	s_addc_u32 s93, s97, 0
	s_add_u32 s40, s91, 0x8000
	s_mov_b32 m0, s40
	s_nop 0
	global_load_lds_dwordx4 v208, s[92:93]
	s_add_u32 s92, s92, 0x2000
	s_addc_u32 s93, s93, 0
	s_add_u32 m0, m0, 0x400
	s_nop 0
	global_load_lds_dwordx4 v208, s[92:93]
	s_add_u32 s92, s92, 0x2000
	s_addc_u32 s93, s93, 0
	s_add_u32 m0, m0, 0x400
	s_nop 0
	global_load_lds_dwordx4 v208, s[92:93]
	s_add_u32 s92, s92, 0x2000
	s_addc_u32 s93, s93, 0
	s_add_u32 m0, m0, 0x400
	s_nop 0
	global_load_lds_dwordx4 v208, s[92:93]
	ds_read_b128 v[160:163], v135 offset:0
	ds_read_b128 v[164:167], v135 offset:16
	ds_read_b128 v[168:171], v135 offset:32
	ds_read_b128 v[172:175], v135 offset:48
	s_waitcnt lgkmcnt(0)
	v_add_f32_e32 v160, v160, v162
	v_add_f32_e32 v161, v161, v163
	v_add_f32_e32 v164, v164, v166
	v_add_f32_e32 v165, v165, v167
	v_add_f32_e32 v168, v168, v170
	v_add_f32_e32 v169, v169, v171
	v_add_f32_e32 v172, v172, v174
	v_add_f32_e32 v173, v173, v175
	v_add_f32_e32 v160, v160, v164
	v_add_f32_e32 v161, v161, v165
	v_add_f32_e32 v168, v168, v172
	v_add_f32_e32 v169, v169, v173
	v_add_f32_e32 v160, v160, v168
	v_add_f32_e32 v161, v161, v169
	v_mul_f32_e32 v192, 0x3a800000, v160
	v_mul_f32_e32 v193, 0x3a800000, v161
	v_fma_f32 v193, -v192, v192, v193
	v_add_f32_e32 v193, 0x3727c5ac, v193
	v_rsq_f32_e32 v193, v193
	s_nop 0
	s_add_u32 s94, s78, 0x10000
	s_addc_u32 s95, s79, 0
	ds_read_b128 v[176:179], v136
	ds_read_b128 v[180:183], v136 offset:4096
	ds_read_b128 v[184:187], v136 offset:64
	ds_read_b128 v[188:191], v136 offset:4160
	s_waitcnt lgkmcnt(2)
	v_sub_f32_e32 v126, v126, v192
	v_mul_f32_e32 v126, v126, v193
	v_fma_f32 v126, v176, v126, v180
	v_sub_f32_e32 v127, v127, v192
	v_mul_f32_e32 v127, v127, v193
	v_fma_f32 v127, v177, v127, v181
	v_sub_f32_e32 v128, v128, v192
	v_mul_f32_e32 v128, v128, v193
	v_fma_f32 v128, v178, v128, v182
	v_sub_f32_e32 v129, v129, v192
	v_mul_f32_e32 v129, v129, v193
	v_fma_f32 v129, v179, v129, v183
	global_store_dwordx4 v137, v[126:129], s[94:95] nt
	ds_read_b128 v[176:179], v136 offset:128
	ds_read_b128 v[180:183], v136 offset:4224
	s_waitcnt lgkmcnt(2)
	v_sub_f32_e32 v122, v122, v192
	v_mul_f32_e32 v122, v122, v193
	v_fma_f32 v122, v184, v122, v188
	v_sub_f32_e32 v123, v123, v192
	v_mul_f32_e32 v123, v123, v193
	v_fma_f32 v123, v185, v123, v189
	v_sub_f32_e32 v124, v124, v192
	v_mul_f32_e32 v124, v124, v193
	v_fma_f32 v124, v186, v124, v190
	v_sub_f32_e32 v125, v125, v192
	v_mul_f32_e32 v125, v125, v193
	v_fma_f32 v125, v187, v125, v191
	global_store_dwordx4 v137, v[122:125], s[94:95] offset:64 nt
	ds_read_b128 v[184:187], v136 offset:192
	ds_read_b128 v[188:191], v136 offset:4288
	s_waitcnt lgkmcnt(2)
	v_sub_f32_e32 v118, v118, v192
	v_mul_f32_e32 v118, v118, v193
	v_fma_f32 v118, v176, v118, v180
	v_sub_f32_e32 v119, v119, v192
	v_mul_f32_e32 v119, v119, v193
	v_fma_f32 v119, v177, v119, v181
	v_sub_f32_e32 v120, v120, v192
	v_mul_f32_e32 v120, v120, v193
	v_fma_f32 v120, v178, v120, v182
	v_sub_f32_e32 v121, v121, v192
	v_mul_f32_e32 v121, v121, v193
	v_fma_f32 v121, v179, v121, v183
	global_store_dwordx4 v137, v[118:121], s[94:95] offset:128 nt
	ds_read_b128 v[176:179], v136 offset:256
	ds_read_b128 v[180:183], v136 offset:4352
	s_waitcnt lgkmcnt(2)
	v_sub_f32_e32 v114, v114, v192
	v_mul_f32_e32 v114, v114, v193
	v_fma_f32 v114, v184, v114, v188
	v_sub_f32_e32 v115, v115, v192
	v_mul_f32_e32 v115, v115, v193
	v_fma_f32 v115, v185, v115, v189
	v_sub_f32_e32 v116, v116, v192
	v_mul_f32_e32 v116, v116, v193
	v_fma_f32 v116, v186, v116, v190
	v_sub_f32_e32 v117, v117, v192
	v_mul_f32_e32 v117, v117, v193
	v_fma_f32 v117, v187, v117, v191
	global_store_dwordx4 v137, v[114:117], s[94:95] offset:192 nt
	ds_read_b128 v[184:187], v136 offset:320
	ds_read_b128 v[188:191], v136 offset:4416
	s_waitcnt lgkmcnt(2)
	v_sub_f32_e32 v110, v110, v192
	v_mul_f32_e32 v110, v110, v193
	v_fma_f32 v110, v176, v110, v180
	v_sub_f32_e32 v111, v111, v192
	v_mul_f32_e32 v111, v111, v193
	v_fma_f32 v111, v177, v111, v181
	v_sub_f32_e32 v112, v112, v192
	v_mul_f32_e32 v112, v112, v193
	v_fma_f32 v112, v178, v112, v182
	v_sub_f32_e32 v113, v113, v192
	v_mul_f32_e32 v113, v113, v193
	v_fma_f32 v113, v179, v113, v183
	global_store_dwordx4 v137, v[110:113], s[94:95] offset:256 nt
	ds_read_b128 v[176:179], v136 offset:384
	ds_read_b128 v[180:183], v136 offset:4480
	s_waitcnt lgkmcnt(2)
	v_sub_f32_e32 v106, v106, v192
	v_mul_f32_e32 v106, v106, v193
	v_fma_f32 v106, v184, v106, v188
	v_sub_f32_e32 v107, v107, v192
	v_mul_f32_e32 v107, v107, v193
	v_fma_f32 v107, v185, v107, v189
	v_sub_f32_e32 v108, v108, v192
	v_mul_f32_e32 v108, v108, v193
	v_fma_f32 v108, v186, v108, v190
	v_sub_f32_e32 v109, v109, v192
	v_mul_f32_e32 v109, v109, v193
	v_fma_f32 v109, v187, v109, v191
	global_store_dwordx4 v137, v[106:109], s[94:95] offset:320 nt
	ds_read_b128 v[184:187], v136 offset:448
	ds_read_b128 v[188:191], v136 offset:4544
	s_waitcnt lgkmcnt(2)
	v_sub_f32_e32 v102, v102, v192
	v_mul_f32_e32 v102, v102, v193
	v_fma_f32 v102, v176, v102, v180
	v_sub_f32_e32 v103, v103, v192
	v_mul_f32_e32 v103, v103, v193
	v_fma_f32 v103, v177, v103, v181
	v_sub_f32_e32 v104, v104, v192
	v_mul_f32_e32 v104, v104, v193
	v_fma_f32 v104, v178, v104, v182
	v_sub_f32_e32 v105, v105, v192
	v_mul_f32_e32 v105, v105, v193
	v_fma_f32 v105, v179, v105, v183
	global_store_dwordx4 v137, v[102:105], s[94:95] offset:384 nt
	s_waitcnt lgkmcnt(0)
	v_sub_f32_e32 v66, v66, v192
	v_mul_f32_e32 v66, v66, v193
	v_fma_f32 v66, v184, v66, v188
	v_sub_f32_e32 v67, v67, v192
	v_mul_f32_e32 v67, v67, v193
	v_fma_f32 v67, v185, v67, v189
	v_sub_f32_e32 v68, v68, v192
	v_mul_f32_e32 v68, v68, v193
	v_fma_f32 v68, v186, v68, v190
	v_sub_f32_e32 v69, v69, v192
	v_mul_f32_e32 v69, v69, v193
	v_fma_f32 v69, v187, v69, v191
	global_store_dwordx4 v137, v[66:69], s[94:95] offset:448 nt
	s_waitcnt vmcnt(20) lgkmcnt(0)
	s_barrier
; DI float bf2f(unsigned b) { return __uint_as_float(b << 16); }
; DI void unit_O(const Params& p, char* lds, int l, int tile, int glu_tiles, int tile_b) {
;     ...
;         float s2[2], ss2[2];
; #pragma unroll
;         for (int mh = 0; mh < 2; ++mh) {
;             const int mt = half * 2 + mh, rl = mh * 16 + l15;
;             float s = 0.f, ss = 0.f;
; #pragma unroll
;             for (int nt = 0; nt < 8; ++nt) {
;                 f32x4 xr;
;                 if (l == 0) {
;                     const int chunk = wid * 32 + nt * 4 + quad;
;                     xr = *(const f32x4*)(XR + rl * 4096 + ((chunk ^ l15) << 4));
;                 } else {
;                     const u32x2 hb = *(const u32x2*)(XR + ((wid * 4 + (nt >> 1)) * 32 + rl) * 64 + (nt & 1) * 32 + quad * 8);
;                     xr = (f32x4){bf2f(hb[0] & 0xffffu), bf2f(hb[0] >> 16), bf2f(hb[1] & 0xffffu), bf2f(hb[1] >> 16)};
;                 }
; #pragma unroll
;                 for (int i = 0; i < 4; ++i) { const float v = acc[mt][nt][i] + DN_ALPHA * xr[i]; acc[mt][nt][i] = v; s += v; ss += v * v; }
;             }
;             s2[mh] = s; ss2[mh] = ss;
;         }
; #pragma unroll
;         for (int mh = 0; mh < 2; ++mh) { s2[mh] += __shfl_xor(s2[mh], 16); ss2[mh] += __shfl_xor(ss2[mh], 16); }
; #pragma unroll
;         for (int mh = 0; mh < 2; ++mh) { s2[mh] += __shfl_xor(s2[mh], 32); ss2[mh] += __shfl_xor(ss2[mh], 32); }
;         if (quad == 0) {
; #pragma unroll
;             for (int mh = 0; mh < 2; ++mh) *(f32x2*)&red[((mh * 16 + l15) * 8 + wid) * 2] = (f32x2){s2[mh], ss2[mh]};
;         }
;         __syncthreads();
	ds_read_b64 v[180:181], v133 offset:0
	ds_read_b64 v[182:183], v133 offset:32
	ds_read_b64 v[184:185], v133 offset:1024
	ds_read_b64 v[186:187], v133 offset:1056
	ds_read_b64 v[188:189], v133 offset:2048
	ds_read_b64 v[190:191], v133 offset:2080
	ds_read_b64 v[192:193], v133 offset:3072
	ds_read_b64 v[194:195], v133 offset:3104
	s_waitcnt lgkmcnt(7)
	v_lshlrev_b32_e32 v144, 16, v180
	v_and_b32_e32 v145, 0xffff0000, v180
	v_lshlrev_b32_e32 v146, 16, v181
	v_and_b32_e32 v147, 0xffff0000, v181
	v_fmac_f32_e32 v34, s58, v144
	v_fmac_f32_e32 v35, s58, v145
	v_fmac_f32_e32 v36, s58, v146
	v_fmac_f32_e32 v37, s58, v147
	v_mov_b32_e32 v196, v34
	v_mul_f32_e32 v197, v34, v34
	v_mov_b32_e32 v130, v35
	v_mul_f32_e32 v142, v35, v35
	v_add_f32_e32 v196, v196, v36
	v_fmac_f32_e32 v197, v36, v36
	v_add_f32_e32 v130, v130, v37
	v_fmac_f32_e32 v142, v37, v37
	s_waitcnt lgkmcnt(6)
	v_lshlrev_b32_e32 v148, 16, v182
	v_and_b32_e32 v149, 0xffff0000, v182
	v_lshlrev_b32_e32 v150, 16, v183
	v_and_b32_e32 v151, 0xffff0000, v183
	v_fmac_f32_e32 v30, s58, v148
	v_fmac_f32_e32 v31, s58, v149
	v_fmac_f32_e32 v32, s58, v150
	v_fmac_f32_e32 v33, s58, v151
	v_add_f32_e32 v196, v196, v30
	v_fmac_f32_e32 v197, v30, v30
	v_add_f32_e32 v130, v130, v31
	v_fmac_f32_e32 v142, v31, v31
	v_add_f32_e32 v196, v196, v32
	v_fmac_f32_e32 v197, v32, v32
	v_add_f32_e32 v130, v130, v33
	v_fmac_f32_e32 v142, v33, v33
	s_waitcnt lgkmcnt(5)
	v_lshlrev_b32_e32 v152, 16, v184
	v_and_b32_e32 v153, 0xffff0000, v184
	v_lshlrev_b32_e32 v154, 16, v185
	v_and_b32_e32 v155, 0xffff0000, v185
	v_fmac_f32_e32 v26, s58, v152
	v_fmac_f32_e32 v27, s58, v153
	v_fmac_f32_e32 v28, s58, v154
	v_fmac_f32_e32 v29, s58, v155
	v_add_f32_e32 v196, v196, v26
	v_fmac_f32_e32 v197, v26, v26
	v_add_f32_e32 v130, v130, v27
	v_fmac_f32_e32 v142, v27, v27
	v_add_f32_e32 v196, v196, v28
	v_fmac_f32_e32 v197, v28, v28
	v_add_f32_e32 v130, v130, v29
	v_fmac_f32_e32 v142, v29, v29
	s_waitcnt lgkmcnt(4)
	v_lshlrev_b32_e32 v156, 16, v186
	v_and_b32_e32 v157, 0xffff0000, v186
	v_lshlrev_b32_e32 v158, 16, v187
	v_and_b32_e32 v159, 0xffff0000, v187
	v_fmac_f32_e32 v22, s58, v156
	v_fmac_f32_e32 v23, s58, v157
	v_fmac_f32_e32 v24, s58, v158
	v_fmac_f32_e32 v25, s58, v159
	v_add_f32_e32 v196, v196, v22
	v_fmac_f32_e32 v197, v22, v22
	v_add_f32_e32 v130, v130, v23
	v_fmac_f32_e32 v142, v23, v23
	v_add_f32_e32 v196, v196, v24
	v_fmac_f32_e32 v197, v24, v24
	v_add_f32_e32 v130, v130, v25
	v_fmac_f32_e32 v142, v25, v25
	s_waitcnt lgkmcnt(3)
	v_lshlrev_b32_e32 v160, 16, v188
	v_and_b32_e32 v161, 0xffff0000, v188
	v_lshlrev_b32_e32 v162, 16, v189
	v_and_b32_e32 v163, 0xffff0000, v189
	v_fmac_f32_e32 v18, s58, v160
	v_fmac_f32_e32 v19, s58, v161
	v_fmac_f32_e32 v20, s58, v162
	v_fmac_f32_e32 v21, s58, v163
	v_add_f32_e32 v196, v196, v18
	v_fmac_f32_e32 v197, v18, v18
	v_add_f32_e32 v130, v130, v19
	v_fmac_f32_e32 v142, v19, v19
	v_add_f32_e32 v196, v196, v20
	v_fmac_f32_e32 v197, v20, v20
	v_add_f32_e32 v130, v130, v21
	v_fmac_f32_e32 v142, v21, v21
	s_waitcnt lgkmcnt(2)
	v_lshlrev_b32_e32 v164, 16, v190
	v_and_b32_e32 v165, 0xffff0000, v190
	v_lshlrev_b32_e32 v166, 16, v191
	v_and_b32_e32 v167, 0xffff0000, v191
	v_fmac_f32_e32 v14, s58, v164
	v_fmac_f32_e32 v15, s58, v165
	v_fmac_f32_e32 v16, s58, v166
	v_fmac_f32_e32 v17, s58, v167
	v_add_f32_e32 v196, v196, v14
	v_fmac_f32_e32 v197, v14, v14
	v_add_f32_e32 v130, v130, v15
	v_fmac_f32_e32 v142, v15, v15
	v_add_f32_e32 v196, v196, v16
	v_fmac_f32_e32 v197, v16, v16
	v_add_f32_e32 v130, v130, v17
	v_fmac_f32_e32 v142, v17, v17
	s_waitcnt lgkmcnt(1)
	v_lshlrev_b32_e32 v168, 16, v192
	v_and_b32_e32 v169, 0xffff0000, v192
	v_lshlrev_b32_e32 v170, 16, v193
	v_and_b32_e32 v171, 0xffff0000, v193
	v_fmac_f32_e32 v10, s58, v168
	v_fmac_f32_e32 v11, s58, v169
	v_fmac_f32_e32 v12, s58, v170
	v_fmac_f32_e32 v13, s58, v171
	v_add_f32_e32 v196, v196, v10
	v_fmac_f32_e32 v197, v10, v10
	v_add_f32_e32 v130, v130, v11
	v_fmac_f32_e32 v142, v11, v11
	v_add_f32_e32 v196, v196, v12
	v_fmac_f32_e32 v197, v12, v12
	v_add_f32_e32 v130, v130, v13
	v_fmac_f32_e32 v142, v13, v13
	s_waitcnt lgkmcnt(0)
	v_lshlrev_b32_e32 v172, 16, v194
	v_and_b32_e32 v173, 0xffff0000, v194
	v_lshlrev_b32_e32 v174, 16, v195
	v_and_b32_e32 v175, 0xffff0000, v195
	v_fmac_f32_e32 v6, s58, v172
	v_fmac_f32_e32 v7, s58, v173
	v_fmac_f32_e32 v8, s58, v174
	v_fmac_f32_e32 v9, s58, v175
	v_add_f32_e32 v196, v196, v6
	v_fmac_f32_e32 v197, v6, v6
	v_add_f32_e32 v130, v130, v7
	v_fmac_f32_e32 v142, v7, v7
	v_add_f32_e32 v196, v196, v8
	v_fmac_f32_e32 v197, v8, v8
	v_add_f32_e32 v130, v130, v9
	v_fmac_f32_e32 v142, v9, v9
	v_add_f32_e32 v196, v196, v130
	v_add_f32_e32 v197, v197, v142
	v_mov_b32_e32 v198, v196
	v_mov_b32_e32 v199, v197
	s_nop 1
	v_permlane16_swap_b32 v198, v196
	v_permlane16_swap_b32 v199, v197
	v_add_f32_e32 v196, v196, v198
	v_add_f32_e32 v197, v197, v199
	v_mov_b32_e32 v198, v196
	v_mov_b32_e32 v199, v197
	s_nop 1
	v_permlane32_swap_b32 v198, v196
	v_permlane32_swap_b32 v199, v197
	v_add_f32_e32 v196, v196, v198
	v_add_f32_e32 v197, v197, v199
	s_mov_b64 exec, 0xffff
	ds_write_b64 v134, v[196:197]
	s_mov_b64 exec, -1
	s_waitcnt lgkmcnt(0)
	s_barrier
; DI unsigned pk2(float lo, float hi) { const f32x2 v = {lo, hi}; const bf16x2_t b = __builtin_convertvector(v, bf16x2_t); return __builtin_bit_cast(unsigned, b); }
; DI size_t xb_off(int tok, int col) { return ((size_t)(((tok >> 7) * 32 + (col >> 5)) * 128 + (tok & 127))) * 32 + (col & 31); }
; DI void unit_O(const Params& p, char* lds, int l, int tile, int glu_tiles, int tile_b) {
;     ...
; #pragma unroll
;         for (int mh = 0; mh < 2; ++mh) {
;             const int mt = half * 2 + mh, rl = mh * 16 + l15, row = mt * 16 + l15;
;             float s = 0.f, ss = 0.f;
; #pragma unroll
;             for (int w = 0; w < 4; ++w) { const f32x4 v = *(const f32x4*)&red[rl * 16 + 4 * w]; s += v[0] + v[2]; ss += v[1] + v[3]; }
;             const float mu = s * (1.f / 1024.f);
;             const float var = ss * (1.f / 1024.f) - mu * mu;
;             const float rs = rsqrtf(var + LN_EPS);
;             float* orow = xo + (r0 + row) * 1024 + wid * 128 + quad * 4;
;             bf16_t* brow = xbo + xb_off((int)r0 + row, wid * 128) + quad * 4;
;             const float* gp = GB + wid * 128 + quad * 4;
; #pragma unroll
;             for (int nt = 0; nt < 8; ++nt) {
;                 const f32x4 g = *(const f32x4*)(gp + nt * 16), bb = *(const f32x4*)(gp + 1024 + nt * 16);
;                 f32x4 o;
; #pragma unroll
;                 for (int i = 0; i < 4; ++i) o[i] = (acc[mt][nt][i] - mu) * rs * g[i] + bb[i];
;                 if (l == 0) *(u32x2*)(brow + (nt >> 1) * 4096 + (nt & 1) * 16) = (u32x2){pk2(o[0], o[1]), pk2(o[2], o[3])};
;                 else *(f32x4*)(orow + nt * 16) = o;
;             }
	ds_read_b128 v[160:163], v135 offset:0
	ds_read_b128 v[164:167], v135 offset:16
	ds_read_b128 v[168:171], v135 offset:32
	ds_read_b128 v[172:175], v135 offset:48
	s_waitcnt lgkmcnt(0)
	v_add_f32_e32 v160, v160, v162
	v_add_f32_e32 v161, v161, v163
	v_add_f32_e32 v164, v164, v166
	v_add_f32_e32 v165, v165, v167
	v_add_f32_e32 v168, v168, v170
	v_add_f32_e32 v169, v169, v171
	v_add_f32_e32 v172, v172, v174
	v_add_f32_e32 v173, v173, v175
	v_add_f32_e32 v160, v160, v164
	v_add_f32_e32 v161, v161, v165
	v_add_f32_e32 v168, v168, v172
	v_add_f32_e32 v169, v169, v173
	v_add_f32_e32 v160, v160, v168
	v_add_f32_e32 v161, v161, v169
	v_mul_f32_e32 v192, 0x3a800000, v160
	v_mul_f32_e32 v193, 0x3a800000, v161
	v_fma_f32 v193, -v192, v192, v193
	v_add_f32_e32 v193, 0x3727c5ac, v193
	v_rsq_f32_e32 v193, v193
	s_nop 0
	s_add_u32 s94, s78, 0x20000
	s_addc_u32 s95, s79, 0
	ds_read_b128 v[176:179], v136
	ds_read_b128 v[180:183], v136 offset:4096
	ds_read_b128 v[184:187], v136 offset:64
	ds_read_b128 v[188:191], v136 offset:4160
	s_waitcnt lgkmcnt(2)
	v_sub_f32_e32 v34, v34, v192
	v_mul_f32_e32 v34, v34, v193
	v_fma_f32 v34, v176, v34, v180
	v_sub_f32_e32 v35, v35, v192
	v_mul_f32_e32 v35, v35, v193
	v_fma_f32 v35, v177, v35, v181
	v_sub_f32_e32 v36, v36, v192
	v_mul_f32_e32 v36, v36, v193
	v_fma_f32 v36, v178, v36, v182
	v_sub_f32_e32 v37, v37, v192
	v_mul_f32_e32 v37, v37, v193
	v_fma_f32 v37, v179, v37, v183
	global_store_dwordx4 v137, v[34:37], s[94:95] nt
	ds_read_b128 v[176:179], v136 offset:128
	ds_read_b128 v[180:183], v136 offset:4224
	s_waitcnt lgkmcnt(2)
	v_sub_f32_e32 v30, v30, v192
	v_mul_f32_e32 v30, v30, v193
	v_fma_f32 v30, v184, v30, v188
	v_sub_f32_e32 v31, v31, v192
	v_mul_f32_e32 v31, v31, v193
	v_fma_f32 v31, v185, v31, v189
	v_sub_f32_e32 v32, v32, v192
	v_mul_f32_e32 v32, v32, v193
	v_fma_f32 v32, v186, v32, v190
	v_sub_f32_e32 v33, v33, v192
	v_mul_f32_e32 v33, v33, v193
	v_fma_f32 v33, v187, v33, v191
	global_store_dwordx4 v137, v[30:33], s[94:95] offset:64 nt
	ds_read_b128 v[184:187], v136 offset:192
	ds_read_b128 v[188:191], v136 offset:4288
	s_waitcnt lgkmcnt(2)
	v_sub_f32_e32 v26, v26, v192
	v_mul_f32_e32 v26, v26, v193
	v_fma_f32 v26, v176, v26, v180
	v_sub_f32_e32 v27, v27, v192
	v_mul_f32_e32 v27, v27, v193
	v_fma_f32 v27, v177, v27, v181
	v_sub_f32_e32 v28, v28, v192
	v_mul_f32_e32 v28, v28, v193
	v_fma_f32 v28, v178, v28, v182
	v_sub_f32_e32 v29, v29, v192
	v_mul_f32_e32 v29, v29, v193
	v_fma_f32 v29, v179, v29, v183
	global_store_dwordx4 v137, v[26:29], s[94:95] offset:128 nt
	ds_read_b128 v[176:179], v136 offset:256
	ds_read_b128 v[180:183], v136 offset:4352
	s_waitcnt lgkmcnt(2)
	v_sub_f32_e32 v22, v22, v192
	v_mul_f32_e32 v22, v22, v193
	v_fma_f32 v22, v184, v22, v188
	v_sub_f32_e32 v23, v23, v192
	v_mul_f32_e32 v23, v23, v193
	v_fma_f32 v23, v185, v23, v189
	v_sub_f32_e32 v24, v24, v192
	v_mul_f32_e32 v24, v24, v193
	v_fma_f32 v24, v186, v24, v190
	v_sub_f32_e32 v25, v25, v192
	v_mul_f32_e32 v25, v25, v193
	v_fma_f32 v25, v187, v25, v191
	global_store_dwordx4 v137, v[22:25], s[94:95] offset:192 nt
	ds_read_b128 v[184:187], v136 offset:320
	ds_read_b128 v[188:191], v136 offset:4416
	s_waitcnt lgkmcnt(2)
	v_sub_f32_e32 v18, v18, v192
	v_mul_f32_e32 v18, v18, v193
	v_fma_f32 v18, v176, v18, v180
	v_sub_f32_e32 v19, v19, v192
	v_mul_f32_e32 v19, v19, v193
	v_fma_f32 v19, v177, v19, v181
	v_sub_f32_e32 v20, v20, v192
	v_mul_f32_e32 v20, v20, v193
	v_fma_f32 v20, v178, v20, v182
	v_sub_f32_e32 v21, v21, v192
	v_mul_f32_e32 v21, v21, v193
	v_fma_f32 v21, v179, v21, v183
	global_store_dwordx4 v137, v[18:21], s[94:95] offset:256 nt
	ds_read_b128 v[176:179], v136 offset:384
	ds_read_b128 v[180:183], v136 offset:4480
	s_waitcnt lgkmcnt(2)
	v_sub_f32_e32 v14, v14, v192
	v_mul_f32_e32 v14, v14, v193
	v_fma_f32 v14, v184, v14, v188
	v_sub_f32_e32 v15, v15, v192
	v_mul_f32_e32 v15, v15, v193
	v_fma_f32 v15, v185, v15, v189
	v_sub_f32_e32 v16, v16, v192
	v_mul_f32_e32 v16, v16, v193
	v_fma_f32 v16, v186, v16, v190
	v_sub_f32_e32 v17, v17, v192
	v_mul_f32_e32 v17, v17, v193
	v_fma_f32 v17, v187, v17, v191
	global_store_dwordx4 v137, v[14:17], s[94:95] offset:320 nt
	ds_read_b128 v[184:187], v136 offset:448
	ds_read_b128 v[188:191], v136 offset:4544
	s_waitcnt lgkmcnt(2)
	v_sub_f32_e32 v10, v10, v192
	v_mul_f32_e32 v10, v10, v193
	v_fma_f32 v10, v176, v10, v180
	v_sub_f32_e32 v11, v11, v192
	v_mul_f32_e32 v11, v11, v193
	v_fma_f32 v11, v177, v11, v181
	v_sub_f32_e32 v12, v12, v192
	v_mul_f32_e32 v12, v12, v193
	v_fma_f32 v12, v178, v12, v182
	v_sub_f32_e32 v13, v13, v192
	v_mul_f32_e32 v13, v13, v193
	v_fma_f32 v13, v179, v13, v183
	global_store_dwordx4 v137, v[10:13], s[94:95] offset:384 nt
	s_waitcnt lgkmcnt(0)
	v_sub_f32_e32 v6, v6, v192
	v_mul_f32_e32 v6, v6, v193
	v_fma_f32 v6, v184, v6, v188
	v_sub_f32_e32 v7, v7, v192
	v_mul_f32_e32 v7, v7, v193
	v_fma_f32 v7, v185, v7, v189
	v_sub_f32_e32 v8, v8, v192
	v_mul_f32_e32 v8, v8, v193
	v_fma_f32 v8, v186, v8, v190
	v_sub_f32_e32 v9, v9, v192
	v_mul_f32_e32 v9, v9, v193
	v_fma_f32 v9, v187, v9, v191
	global_store_dwordx4 v137, v[6:9], s[94:95] offset:448 nt
	s_waitcnt vmcnt(16) lgkmcnt(0)
	s_barrier
; DI float bf2f(unsigned b) { return __uint_as_float(b << 16); }
; DI void unit_O(const Params& p, char* lds, int l, int tile, int glu_tiles, int tile_b) {
;     ...
;         float s2[2], ss2[2];
; #pragma unroll
;         for (int mh = 0; mh < 2; ++mh) {
;             const int mt = half * 2 + mh, rl = mh * 16 + l15;
;             float s = 0.f, ss = 0.f;
; #pragma unroll
;             for (int nt = 0; nt < 8; ++nt) {
;                 f32x4 xr;
;                 if (l == 0) {
;                     const int chunk = wid * 32 + nt * 4 + quad;
;                     xr = *(const f32x4*)(XR + rl * 4096 + ((chunk ^ l15) << 4));
;                 } else {
;                     const u32x2 hb = *(const u32x2*)(XR + ((wid * 4 + (nt >> 1)) * 32 + rl) * 64 + (nt & 1) * 32 + quad * 8);
;                     xr = (f32x4){bf2f(hb[0] & 0xffffu), bf2f(hb[0] >> 16), bf2f(hb[1] & 0xffffu), bf2f(hb[1] >> 16)};
;                 }
; #pragma unroll
;                 for (int i = 0; i < 4; ++i) { const float v = acc[mt][nt][i] + DN_ALPHA * xr[i]; acc[mt][nt][i] = v; s += v; ss += v * v; }
;             }
;             s2[mh] = s; ss2[mh] = ss;
;         }
; #pragma unroll
;         for (int mh = 0; mh < 2; ++mh) { s2[mh] += __shfl_xor(s2[mh], 16); ss2[mh] += __shfl_xor(ss2[mh], 16); }
; #pragma unroll
;         for (int mh = 0; mh < 2; ++mh) { s2[mh] += __shfl_xor(s2[mh], 32); ss2[mh] += __shfl_xor(ss2[mh], 32); }
;         if (quad == 0) {
; #pragma unroll
;             for (int mh = 0; mh < 2; ++mh) *(f32x2*)&red[((mh * 16 + l15) * 8 + wid) * 2] = (f32x2){s2[mh], ss2[mh]};
;         }
;         __syncthreads();
	ds_read_b64 v[180:181], v133 offset:32768
	ds_read_b64 v[182:183], v133 offset:32800
	ds_read_b64 v[184:185], v133 offset:33792
	ds_read_b64 v[186:187], v133 offset:33824
	ds_read_b64 v[188:189], v133 offset:34816
	ds_read_b64 v[190:191], v133 offset:34848
	ds_read_b64 v[192:193], v133 offset:35840
	ds_read_b64 v[194:195], v133 offset:35872
	s_waitcnt lgkmcnt(7)
	v_lshlrev_b32_e32 v144, 16, v180
	v_and_b32_e32 v145, 0xffff0000, v180
	v_lshlrev_b32_e32 v146, 16, v181
	v_and_b32_e32 v147, 0xffff0000, v181
	v_fmac_f32_e32 v62, s58, v144
	v_fmac_f32_e32 v63, s58, v145
	v_fmac_f32_e32 v64, s58, v146
	v_fmac_f32_e32 v65, s58, v147
	v_mov_b32_e32 v196, v62
	v_mul_f32_e32 v197, v62, v62
	v_mov_b32_e32 v130, v63
	v_mul_f32_e32 v142, v63, v63
	v_add_f32_e32 v196, v196, v64
	v_fmac_f32_e32 v197, v64, v64
	v_add_f32_e32 v130, v130, v65
	v_fmac_f32_e32 v142, v65, v65
	s_waitcnt lgkmcnt(6)
	v_lshlrev_b32_e32 v148, 16, v182
	v_and_b32_e32 v149, 0xffff0000, v182
	v_lshlrev_b32_e32 v150, 16, v183
	v_and_b32_e32 v151, 0xffff0000, v183
	v_fmac_f32_e32 v58, s58, v148
	v_fmac_f32_e32 v59, s58, v149
	v_fmac_f32_e32 v60, s58, v150
	v_fmac_f32_e32 v61, s58, v151
	v_add_f32_e32 v196, v196, v58
	v_fmac_f32_e32 v197, v58, v58
	v_add_f32_e32 v130, v130, v59
	v_fmac_f32_e32 v142, v59, v59
	v_add_f32_e32 v196, v196, v60
	v_fmac_f32_e32 v197, v60, v60
	v_add_f32_e32 v130, v130, v61
	v_fmac_f32_e32 v142, v61, v61
	s_waitcnt lgkmcnt(5)
	v_lshlrev_b32_e32 v152, 16, v184
	v_and_b32_e32 v153, 0xffff0000, v184
	v_lshlrev_b32_e32 v154, 16, v185
	v_and_b32_e32 v155, 0xffff0000, v185
	v_fmac_f32_e32 v54, s58, v152
	v_fmac_f32_e32 v55, s58, v153
	v_fmac_f32_e32 v56, s58, v154
	v_fmac_f32_e32 v57, s58, v155
	v_add_f32_e32 v196, v196, v54
	v_fmac_f32_e32 v197, v54, v54
	v_add_f32_e32 v130, v130, v55
	v_fmac_f32_e32 v142, v55, v55
	v_add_f32_e32 v196, v196, v56
	v_fmac_f32_e32 v197, v56, v56
	v_add_f32_e32 v130, v130, v57
	v_fmac_f32_e32 v142, v57, v57
	s_waitcnt lgkmcnt(4)
	v_lshlrev_b32_e32 v156, 16, v186
	v_and_b32_e32 v157, 0xffff0000, v186
	v_lshlrev_b32_e32 v158, 16, v187
	v_and_b32_e32 v159, 0xffff0000, v187
	v_fmac_f32_e32 v50, s58, v156
	v_fmac_f32_e32 v51, s58, v157
	v_fmac_f32_e32 v52, s58, v158
	v_fmac_f32_e32 v53, s58, v159
	v_add_f32_e32 v196, v196, v50
	v_fmac_f32_e32 v197, v50, v50
	v_add_f32_e32 v130, v130, v51
	v_fmac_f32_e32 v142, v51, v51
	v_add_f32_e32 v196, v196, v52
	v_fmac_f32_e32 v197, v52, v52
	v_add_f32_e32 v130, v130, v53
	v_fmac_f32_e32 v142, v53, v53
	s_waitcnt lgkmcnt(3)
	v_lshlrev_b32_e32 v160, 16, v188
	v_and_b32_e32 v161, 0xffff0000, v188
	v_lshlrev_b32_e32 v162, 16, v189
	v_and_b32_e32 v163, 0xffff0000, v189
	v_fmac_f32_e32 v46, s58, v160
	v_fmac_f32_e32 v47, s58, v161
	v_fmac_f32_e32 v48, s58, v162
	v_fmac_f32_e32 v49, s58, v163
	v_add_f32_e32 v196, v196, v46
	v_fmac_f32_e32 v197, v46, v46
	v_add_f32_e32 v130, v130, v47
	v_fmac_f32_e32 v142, v47, v47
	v_add_f32_e32 v196, v196, v48
	v_fmac_f32_e32 v197, v48, v48
	v_add_f32_e32 v130, v130, v49
	v_fmac_f32_e32 v142, v49, v49
	s_waitcnt lgkmcnt(2)
	v_lshlrev_b32_e32 v164, 16, v190
	v_and_b32_e32 v165, 0xffff0000, v190
	v_lshlrev_b32_e32 v166, 16, v191
	v_and_b32_e32 v167, 0xffff0000, v191
	v_fmac_f32_e32 v42, s58, v164
	v_fmac_f32_e32 v43, s58, v165
	v_fmac_f32_e32 v44, s58, v166
	v_fmac_f32_e32 v45, s58, v167
	v_add_f32_e32 v196, v196, v42
	v_fmac_f32_e32 v197, v42, v42
	v_add_f32_e32 v130, v130, v43
	v_fmac_f32_e32 v142, v43, v43
	v_add_f32_e32 v196, v196, v44
	v_fmac_f32_e32 v197, v44, v44
	v_add_f32_e32 v130, v130, v45
	v_fmac_f32_e32 v142, v45, v45
	s_waitcnt lgkmcnt(1)
	v_lshlrev_b32_e32 v168, 16, v192
	v_and_b32_e32 v169, 0xffff0000, v192
	v_lshlrev_b32_e32 v170, 16, v193
	v_and_b32_e32 v171, 0xffff0000, v193
	v_fmac_f32_e32 v38, s58, v168
	v_fmac_f32_e32 v39, s58, v169
	v_fmac_f32_e32 v40, s58, v170
	v_fmac_f32_e32 v41, s58, v171
	v_add_f32_e32 v196, v196, v38
	v_fmac_f32_e32 v197, v38, v38
	v_add_f32_e32 v130, v130, v39
	v_fmac_f32_e32 v142, v39, v39
	v_add_f32_e32 v196, v196, v40
	v_fmac_f32_e32 v197, v40, v40
	v_add_f32_e32 v130, v130, v41
	v_fmac_f32_e32 v142, v41, v41
	s_waitcnt lgkmcnt(0)
	v_lshlrev_b32_e32 v172, 16, v194
	v_and_b32_e32 v173, 0xffff0000, v194
	v_lshlrev_b32_e32 v174, 16, v195
	v_and_b32_e32 v175, 0xffff0000, v195
	v_fmac_f32_e32 v2, s58, v172
	v_fmac_f32_e32 v3, s58, v173
	v_fmac_f32_e32 v4, s58, v174
	v_fmac_f32_e32 v5, s58, v175
	v_add_f32_e32 v196, v196, v2
	v_fmac_f32_e32 v197, v2, v2
	v_add_f32_e32 v130, v130, v3
	v_fmac_f32_e32 v142, v3, v3
	v_add_f32_e32 v196, v196, v4
	v_fmac_f32_e32 v197, v4, v4
	v_add_f32_e32 v130, v130, v5
	v_fmac_f32_e32 v142, v5, v5
	v_add_f32_e32 v196, v196, v130
	v_add_f32_e32 v197, v197, v142
	v_mov_b32_e32 v198, v196
	v_mov_b32_e32 v199, v197
	s_nop 1
	v_permlane16_swap_b32 v198, v196
	v_permlane16_swap_b32 v199, v197
	v_add_f32_e32 v196, v196, v198
	v_add_f32_e32 v197, v197, v199
	v_mov_b32_e32 v198, v196
	v_mov_b32_e32 v199, v197
	s_nop 1
	v_permlane32_swap_b32 v198, v196
	v_permlane32_swap_b32 v199, v197
	v_add_f32_e32 v196, v196, v198
	v_add_f32_e32 v197, v197, v199
	s_mov_b64 exec, 0xffff
	ds_write_b64 v134, v[196:197]
	s_mov_b64 exec, -1
	s_waitcnt lgkmcnt(0)
	s_barrier
; DI unsigned pk2(float lo, float hi) { const f32x2 v = {lo, hi}; const bf16x2_t b = __builtin_convertvector(v, bf16x2_t); return __builtin_bit_cast(unsigned, b); }
; DI size_t xb_off(int tok, int col) { return ((size_t)(((tok >> 7) * 32 + (col >> 5)) * 128 + (tok & 127))) * 32 + (col & 31); }
; DI void unit_O(const Params& p, char* lds, int l, int tile, int glu_tiles, int tile_b) {
;     ...
; #pragma unroll
;         for (int mh = 0; mh < 2; ++mh) {
;             const int mt = half * 2 + mh, rl = mh * 16 + l15, row = mt * 16 + l15;
;             float s = 0.f, ss = 0.f;
; #pragma unroll
;             for (int w = 0; w < 4; ++w) { const f32x4 v = *(const f32x4*)&red[rl * 16 + 4 * w]; s += v[0] + v[2]; ss += v[1] + v[3]; }
;             const float mu = s * (1.f / 1024.f);
;             const float var = ss * (1.f / 1024.f) - mu * mu;
;             const float rs = rsqrtf(var + LN_EPS);
;             float* orow = xo + (r0 + row) * 1024 + wid * 128 + quad * 4;
;             bf16_t* brow = xbo + xb_off((int)r0 + row, wid * 128) + quad * 4;
;             const float* gp = GB + wid * 128 + quad * 4;
; #pragma unroll
;             for (int nt = 0; nt < 8; ++nt) {
;                 const f32x4 g = *(const f32x4*)(gp + nt * 16), bb = *(const f32x4*)(gp + 1024 + nt * 16);
;                 f32x4 o;
; #pragma unroll
;                 for (int i = 0; i < 4; ++i) o[i] = (acc[mt][nt][i] - mu) * rs * g[i] + bb[i];
;                 if (l == 0) *(u32x2*)(brow + (nt >> 1) * 4096 + (nt & 1) * 16) = (u32x2){pk2(o[0], o[1]), pk2(o[2], o[3])};
;                 else *(f32x4*)(orow + nt * 16) = o;
;             }
	ds_read_b128 v[160:163], v135 offset:0
	ds_read_b128 v[164:167], v135 offset:16
	ds_read_b128 v[168:171], v135 offset:32
	ds_read_b128 v[172:175], v135 offset:48
	s_waitcnt lgkmcnt(0)
	v_add_f32_e32 v160, v160, v162
	v_add_f32_e32 v161, v161, v163
	v_add_f32_e32 v164, v164, v166
	v_add_f32_e32 v165, v165, v167
	v_add_f32_e32 v168, v168, v170
	v_add_f32_e32 v169, v169, v171
	v_add_f32_e32 v172, v172, v174
	v_add_f32_e32 v173, v173, v175
	v_add_f32_e32 v160, v160, v164
	v_add_f32_e32 v161, v161, v165
	v_add_f32_e32 v168, v168, v172
	v_add_f32_e32 v169, v169, v173
	v_add_f32_e32 v160, v160, v168
	v_add_f32_e32 v161, v161, v169
	v_mul_f32_e32 v192, 0x3a800000, v160
	v_mul_f32_e32 v193, 0x3a800000, v161
	v_fma_f32 v193, -v192, v192, v193
	v_add_f32_e32 v193, 0x3727c5ac, v193
	v_rsq_f32_e32 v193, v193
	s_nop 0
	s_add_u32 s94, s78, 0x30000
	s_addc_u32 s95, s79, 0
	ds_read_b128 v[176:179], v136
	ds_read_b128 v[180:183], v136 offset:4096
	ds_read_b128 v[184:187], v136 offset:64
	ds_read_b128 v[188:191], v136 offset:4160
	s_waitcnt lgkmcnt(2)
	v_sub_f32_e32 v62, v62, v192
	v_mul_f32_e32 v62, v62, v193
	v_fma_f32 v62, v176, v62, v180
	v_sub_f32_e32 v63, v63, v192
	v_mul_f32_e32 v63, v63, v193
	v_fma_f32 v63, v177, v63, v181
	v_sub_f32_e32 v64, v64, v192
	v_mul_f32_e32 v64, v64, v193
	v_fma_f32 v64, v178, v64, v182
	v_sub_f32_e32 v65, v65, v192
	v_mul_f32_e32 v65, v65, v193
	v_fma_f32 v65, v179, v65, v183
	global_store_dwordx4 v137, v[62:65], s[94:95] nt
	ds_read_b128 v[176:179], v136 offset:128
	ds_read_b128 v[180:183], v136 offset:4224
	s_waitcnt lgkmcnt(2)
	v_sub_f32_e32 v58, v58, v192
	v_mul_f32_e32 v58, v58, v193
	v_fma_f32 v58, v184, v58, v188
	v_sub_f32_e32 v59, v59, v192
	v_mul_f32_e32 v59, v59, v193
	v_fma_f32 v59, v185, v59, v189
	v_sub_f32_e32 v60, v60, v192
	v_mul_f32_e32 v60, v60, v193
	v_fma_f32 v60, v186, v60, v190
	v_sub_f32_e32 v61, v61, v192
	v_mul_f32_e32 v61, v61, v193
	v_fma_f32 v61, v187, v61, v191
	global_store_dwordx4 v137, v[58:61], s[94:95] offset:64 nt
	ds_read_b128 v[184:187], v136 offset:192
	ds_read_b128 v[188:191], v136 offset:4288
	s_waitcnt lgkmcnt(2)
	v_sub_f32_e32 v54, v54, v192
	v_mul_f32_e32 v54, v54, v193
	v_fma_f32 v54, v176, v54, v180
	v_sub_f32_e32 v55, v55, v192
	v_mul_f32_e32 v55, v55, v193
	v_fma_f32 v55, v177, v55, v181
	v_sub_f32_e32 v56, v56, v192
	v_mul_f32_e32 v56, v56, v193
	v_fma_f32 v56, v178, v56, v182
	v_sub_f32_e32 v57, v57, v192
	v_mul_f32_e32 v57, v57, v193
	v_fma_f32 v57, v179, v57, v183
	global_store_dwordx4 v137, v[54:57], s[94:95] offset:128 nt
	ds_read_b128 v[176:179], v136 offset:256
	ds_read_b128 v[180:183], v136 offset:4352
	s_waitcnt lgkmcnt(2)
	v_sub_f32_e32 v50, v50, v192
	v_mul_f32_e32 v50, v50, v193
	v_fma_f32 v50, v184, v50, v188
	v_sub_f32_e32 v51, v51, v192
	v_mul_f32_e32 v51, v51, v193
	v_fma_f32 v51, v185, v51, v189
	v_sub_f32_e32 v52, v52, v192
	v_mul_f32_e32 v52, v52, v193
	v_fma_f32 v52, v186, v52, v190
	v_sub_f32_e32 v53, v53, v192
	v_mul_f32_e32 v53, v53, v193
	v_fma_f32 v53, v187, v53, v191
	global_store_dwordx4 v137, v[50:53], s[94:95] offset:192 nt
	ds_read_b128 v[184:187], v136 offset:320
	ds_read_b128 v[188:191], v136 offset:4416
	s_waitcnt lgkmcnt(2)
	v_sub_f32_e32 v46, v46, v192
	v_mul_f32_e32 v46, v46, v193
	v_fma_f32 v46, v176, v46, v180
	v_sub_f32_e32 v47, v47, v192
	v_mul_f32_e32 v47, v47, v193
	v_fma_f32 v47, v177, v47, v181
	v_sub_f32_e32 v48, v48, v192
	v_mul_f32_e32 v48, v48, v193
	v_fma_f32 v48, v178, v48, v182
	v_sub_f32_e32 v49, v49, v192
	v_mul_f32_e32 v49, v49, v193
	v_fma_f32 v49, v179, v49, v183
	global_store_dwordx4 v137, v[46:49], s[94:95] offset:256 nt
	ds_read_b128 v[176:179], v136 offset:384
	ds_read_b128 v[180:183], v136 offset:4480
	s_waitcnt lgkmcnt(2)
	v_sub_f32_e32 v42, v42, v192
	v_mul_f32_e32 v42, v42, v193
	v_fma_f32 v42, v184, v42, v188
	v_sub_f32_e32 v43, v43, v192
	v_mul_f32_e32 v43, v43, v193
	v_fma_f32 v43, v185, v43, v189
	v_sub_f32_e32 v44, v44, v192
	v_mul_f32_e32 v44, v44, v193
	v_fma_f32 v44, v186, v44, v190
	v_sub_f32_e32 v45, v45, v192
	v_mul_f32_e32 v45, v45, v193
	v_fma_f32 v45, v187, v45, v191
	global_store_dwordx4 v137, v[42:45], s[94:95] offset:320 nt
	ds_read_b128 v[184:187], v136 offset:448
	ds_read_b128 v[188:191], v136 offset:4544
	s_waitcnt lgkmcnt(2)
	v_sub_f32_e32 v38, v38, v192
	v_mul_f32_e32 v38, v38, v193
	v_fma_f32 v38, v176, v38, v180
	v_sub_f32_e32 v39, v39, v192
	v_mul_f32_e32 v39, v39, v193
	v_fma_f32 v39, v177, v39, v181
	v_sub_f32_e32 v40, v40, v192
	v_mul_f32_e32 v40, v40, v193
	v_fma_f32 v40, v178, v40, v182
	v_sub_f32_e32 v41, v41, v192
	v_mul_f32_e32 v41, v41, v193
	v_fma_f32 v41, v179, v41, v183
	global_store_dwordx4 v137, v[38:41], s[94:95] offset:384 nt
	s_waitcnt lgkmcnt(0)
	v_sub_f32_e32 v2, v2, v192
	v_mul_f32_e32 v2, v2, v193
	v_fma_f32 v2, v184, v2, v188
	v_sub_f32_e32 v3, v3, v192
	v_mul_f32_e32 v3, v3, v193
	v_fma_f32 v3, v185, v3, v189
	v_sub_f32_e32 v4, v4, v192
	v_mul_f32_e32 v4, v4, v193
	v_fma_f32 v4, v186, v4, v190
	v_sub_f32_e32 v5, v5, v192
	v_mul_f32_e32 v5, v5, v193
	v_fma_f32 v5, v187, v5, v191
	global_store_dwordx4 v137, v[2:5], s[94:95] offset:448 nt

; DI float bf2f(unsigned b) { return __uint_as_float(b << 16); }
; DI void unit_O(const Params& p, char* lds, int l, int tile, int glu_tiles, int tile_b) {
;     ...
;     const bf16_t* xbres = WS_PTR(const bf16_t, OFF_XB1) + ((size_t)((tile >> 1) * 32) * 128 + (tile & 1) * 64) * 32;
;     auto issue_x = [&](int half) {
;         if (l == 0) {
; #pragma unroll 1
;             for (int i = 0; i < 16; ++i) {
;                 const int pc = (wid * 16 + i + xrot) & 127, row = pc >> 2, phys = (pc & 3) * 64 + lane, logical = phys ^ (row & 15);
;                 __builtin_amdgcn_global_load_lds((const unsigned*)(xres + (r0 + half * 32 + row) * 1024 + logical * 4), (unsigned*)(XR + pc * 1024 + lane * 16), 16, 0, 0);
;             }
;         } else {
; #pragma unroll 1
;             for (int i = 0; i < 8; ++i) {
;                 const int pc = (wid * 8 + i + (xrot >> 1)) & 63, kt = pc >> 1, sub = pc & 1;
;     ...
;         float s2[2], ss2[2];
; #pragma unroll
;         for (int mh = 0; mh < 2; ++mh) {
;             const int mt = half * 2 + mh, rl = mh * 16 + l15;
;             float s = 0.f, ss = 0.f;
; #pragma unroll
;             for (int nt = 0; nt < 8; ++nt) {
;                 f32x4 xr;
;                 if (l == 0) {
;                     const int chunk = wid * 32 + nt * 4 + quad;
;                     xr = *(const f32x4*)(XR + rl * 4096 + ((chunk ^ l15) << 4));
;                 } else {
;                     const u32x2 hb = *(const u32x2*)(XR + ((wid * 4 + (nt >> 1)) * 32 + rl) * 64 + (nt & 1) * 32 + quad * 8);
;                     xr = (f32x4){bf2f(hb[0] & 0xffffu), bf2f(hb[0] >> 16), bf2f(hb[1] & 0xffffu), bf2f(hb[1] >> 16)};
;                 }
; #pragma unroll
;                 for (int i = 0; i < 4; ++i) { const float v = acc[mt][nt][i] + DN_ALPHA * xr[i]; acc[mt][nt][i] = v; s += v; ss += v * v; }
;             }
;             s2[mh] = s; ss2[mh] = ss;
;         }
; #pragma unroll
;         for (int mh = 0; mh < 2; ++mh) { s2[mh] += __shfl_xor(s2[mh], 16); ss2[mh] += __shfl_xor(ss2[mh], 16); }
; #pragma unroll
;         for (int mh = 0; mh < 2; ++mh) { s2[mh] += __shfl_xor(s2[mh], 32); ss2[mh] += __shfl_xor(ss2[mh], 32); }
;         if (quad == 0) {
; #pragma unroll
;             for (int mh = 0; mh < 2; ++mh) *(f32x2*)&red[((mh * 16 + l15) * 8 + wid) * 2] = (f32x2){s2[mh], ss2[mh]};
;         }
;         __syncthreads();
.Le2_l1:
	s_lshr_b32 s40, s48, 1
	s_lshl_b32 s40, s40, 18
	s_and_b32 s94, s48, 1
	s_lshl_b32 s94, s94, 12
	s_add_u32 s40, s40, s94
	s_lshl_b32 s91, s90, 12
	s_lshl_b32 s94, s90, 15
	s_add_u32 s96, s56, s40
	s_addc_u32 s97, s57, 0
	s_add_u32 s96, s96, s94
	s_addc_u32 s97, s97, 0
	v_lshlrev_b32_e32 v208, 4, v141
	v_lshlrev_b32_e32 v133, 12, v140
	v_lshl_add_u32 v133, v138, 6, v133
	v_lshl_add_u32 v133, v139, 3, v133
	v_lshlrev_b32_e32 v137, 12, v138
	v_lshl_add_u32 v137, v140, 9, v137
	v_lshl_add_u32 v137, v139, 4, v137
	s_lshl_b32 s40, s48, 18
	s_add_u32 s78, s16, s40
	s_addc_u32 s79, s17, 0
	s_add_u32 s92, s96, 0x0
	s_addc_u32 s93, s97, 0
	s_add_u32 s40, s91, 0x0
	s_mov_b32 m0, s40
	s_nop 0
	global_load_lds_dwordx4 v208, s[92:93]
	s_add_u32 s92, s92, 0x2000
	s_addc_u32 s93, s93, 0
	s_add_u32 m0, m0, 0x400
	s_nop 0
	global_load_lds_dwordx4 v208, s[92:93]
	s_add_u32 s92, s92, 0x2000
	s_addc_u32 s93, s93, 0
	s_add_u32 m0, m0, 0x400
	s_nop 0
	global_load_lds_dwordx4 v208, s[92:93]
	s_add_u32 s92, s92, 0x2000
	s_addc_u32 s93, s93, 0
	s_add_u32 m0, m0, 0x400
	s_nop 0
	global_load_lds_dwordx4 v208, s[92:93]
	s_add_u32 s92, s96, 0x400
	s_addc_u32 s93, s97, 0
	s_add_u32 s40, s91, 0x8000
	s_mov_b32 m0, s40
	s_nop 0
	global_load_lds_dwordx4 v208, s[92:93]
	s_add_u32 s92, s92, 0x2000
	s_addc_u32 s93, s93, 0
	s_add_u32 m0, m0, 0x400
	s_nop 0
	global_load_lds_dwordx4 v208, s[92:93]
	s_add_u32 s92, s92, 0x2000
	s_addc_u32 s93, s93, 0
	s_add_u32 m0, m0, 0x400
	s_nop 0
	global_load_lds_dwordx4 v208, s[92:93]
	s_add_u32 s92, s92, 0x2000
	s_addc_u32 s93, s93, 0
	s_add_u32 m0, m0, 0x400
	s_nop 0
	global_load_lds_dwordx4 v208, s[92:93]
	s_waitcnt vmcnt(8)
	ds_write_b128 v143, v[176:179]
	s_waitcnt vmcnt(4) lgkmcnt(0)
	s_barrier
	ds_read_b64 v[180:181], v133 offset:0
	ds_read_b64 v[182:183], v133 offset:32
	ds_read_b64 v[184:185], v133 offset:1024
	ds_read_b64 v[186:187], v133 offset:1056
	ds_read_b64 v[188:189], v133 offset:2048
	ds_read_b64 v[190:191], v133 offset:2080
	ds_read_b64 v[192:193], v133 offset:3072
	ds_read_b64 v[194:195], v133 offset:3104
	s_waitcnt lgkmcnt(7)
	v_lshlrev_b32_e32 v144, 16, v180
	v_and_b32_e32 v145, 0xffff0000, v180
	v_lshlrev_b32_e32 v146, 16, v181
	v_and_b32_e32 v147, 0xffff0000, v181
	v_fmac_f32_e32 v98, s58, v144
	v_fmac_f32_e32 v99, s58, v145
	v_fmac_f32_e32 v100, s58, v146
	v_fmac_f32_e32 v101, s58, v147
	v_mov_b32_e32 v196, v98
	v_mul_f32_e32 v197, v98, v98
	v_mov_b32_e32 v130, v99
	v_mul_f32_e32 v142, v99, v99
	v_add_f32_e32 v196, v196, v100
	v_fmac_f32_e32 v197, v100, v100
	v_add_f32_e32 v130, v130, v101
	v_fmac_f32_e32 v142, v101, v101
	s_waitcnt lgkmcnt(6)
	v_lshlrev_b32_e32 v148, 16, v182
	v_and_b32_e32 v149, 0xffff0000, v182
	v_lshlrev_b32_e32 v150, 16, v183
	v_and_b32_e32 v151, 0xffff0000, v183
	v_fmac_f32_e32 v94, s58, v148
	v_fmac_f32_e32 v95, s58, v149
	v_fmac_f32_e32 v96, s58, v150
	v_fmac_f32_e32 v97, s58, v151
	v_add_f32_e32 v196, v196, v94
	v_fmac_f32_e32 v197, v94, v94
	v_add_f32_e32 v130, v130, v95
	v_fmac_f32_e32 v142, v95, v95
	v_add_f32_e32 v196, v196, v96
	v_fmac_f32_e32 v197, v96, v96
	v_add_f32_e32 v130, v130, v97
	v_fmac_f32_e32 v142, v97, v97
	s_waitcnt lgkmcnt(5)
	v_lshlrev_b32_e32 v152, 16, v184
	v_and_b32_e32 v153, 0xffff0000, v184
	v_lshlrev_b32_e32 v154, 16, v185
	v_and_b32_e32 v155, 0xffff0000, v185
	v_fmac_f32_e32 v90, s58, v152
	v_fmac_f32_e32 v91, s58, v153
	v_fmac_f32_e32 v92, s58, v154
	v_fmac_f32_e32 v93, s58, v155
	v_add_f32_e32 v196, v196, v90
	v_fmac_f32_e32 v197, v90, v90
	v_add_f32_e32 v130, v130, v91
	v_fmac_f32_e32 v142, v91, v91
	v_add_f32_e32 v196, v196, v92
	v_fmac_f32_e32 v197, v92, v92
	v_add_f32_e32 v130, v130, v93
	v_fmac_f32_e32 v142, v93, v93
	s_waitcnt lgkmcnt(4)
	v_lshlrev_b32_e32 v156, 16, v186
	v_and_b32_e32 v157, 0xffff0000, v186
	v_lshlrev_b32_e32 v158, 16, v187
	v_and_b32_e32 v159, 0xffff0000, v187
	v_fmac_f32_e32 v86, s58, v156
	v_fmac_f32_e32 v87, s58, v157
	v_fmac_f32_e32 v88, s58, v158
	v_fmac_f32_e32 v89, s58, v159
	v_add_f32_e32 v196, v196, v86
	v_fmac_f32_e32 v197, v86, v86
	v_add_f32_e32 v130, v130, v87
	v_fmac_f32_e32 v142, v87, v87
	v_add_f32_e32 v196, v196, v88
	v_fmac_f32_e32 v197, v88, v88
	v_add_f32_e32 v130, v130, v89
	v_fmac_f32_e32 v142, v89, v89
	s_waitcnt lgkmcnt(3)
	v_lshlrev_b32_e32 v160, 16, v188
	v_and_b32_e32 v161, 0xffff0000, v188
	v_lshlrev_b32_e32 v162, 16, v189
	v_and_b32_e32 v163, 0xffff0000, v189
	v_fmac_f32_e32 v82, s58, v160
	v_fmac_f32_e32 v83, s58, v161
	v_fmac_f32_e32 v84, s58, v162
	v_fmac_f32_e32 v85, s58, v163
	v_add_f32_e32 v196, v196, v82
	v_fmac_f32_e32 v197, v82, v82
	v_add_f32_e32 v130, v130, v83
	v_fmac_f32_e32 v142, v83, v83
	v_add_f32_e32 v196, v196, v84
	v_fmac_f32_e32 v197, v84, v84
	v_add_f32_e32 v130, v130, v85
	v_fmac_f32_e32 v142, v85, v85
	s_waitcnt lgkmcnt(2)
	v_lshlrev_b32_e32 v164, 16, v190
	v_and_b32_e32 v165, 0xffff0000, v190
	v_lshlrev_b32_e32 v166, 16, v191
	v_and_b32_e32 v167, 0xffff0000, v191
	v_fmac_f32_e32 v78, s58, v164
	v_fmac_f32_e32 v79, s58, v165
	v_fmac_f32_e32 v80, s58, v166
	v_fmac_f32_e32 v81, s58, v167
	v_add_f32_e32 v196, v196, v78
	v_fmac_f32_e32 v197, v78, v78
	v_add_f32_e32 v130, v130, v79
	v_fmac_f32_e32 v142, v79, v79
	v_add_f32_e32 v196, v196, v80
	v_fmac_f32_e32 v197, v80, v80
	v_add_f32_e32 v130, v130, v81
	v_fmac_f32_e32 v142, v81, v81
	s_waitcnt lgkmcnt(1)
	v_lshlrev_b32_e32 v168, 16, v192
	v_and_b32_e32 v169, 0xffff0000, v192
	v_lshlrev_b32_e32 v170, 16, v193
	v_and_b32_e32 v171, 0xffff0000, v193
	v_fmac_f32_e32 v74, s58, v168
	v_fmac_f32_e32 v75, s58, v169
	v_fmac_f32_e32 v76, s58, v170
	v_fmac_f32_e32 v77, s58, v171
	v_add_f32_e32 v196, v196, v74
	v_fmac_f32_e32 v197, v74, v74
	v_add_f32_e32 v130, v130, v75
	v_fmac_f32_e32 v142, v75, v75
	v_add_f32_e32 v196, v196, v76
	v_fmac_f32_e32 v197, v76, v76
	v_add_f32_e32 v130, v130, v77
	v_fmac_f32_e32 v142, v77, v77
	s_waitcnt lgkmcnt(0)
	v_lshlrev_b32_e32 v172, 16, v194
	v_and_b32_e32 v173, 0xffff0000, v194
	v_lshlrev_b32_e32 v174, 16, v195
	v_and_b32_e32 v175, 0xffff0000, v195
	v_fmac_f32_e32 v70, s58, v172
	v_fmac_f32_e32 v71, s58, v173
	v_fmac_f32_e32 v72, s58, v174
	v_fmac_f32_e32 v73, s58, v175
	v_add_f32_e32 v196, v196, v70
	v_fmac_f32_e32 v197, v70, v70
	v_add_f32_e32 v130, v130, v71
	v_fmac_f32_e32 v142, v71, v71
	v_add_f32_e32 v196, v196, v72
	v_fmac_f32_e32 v197, v72, v72
	v_add_f32_e32 v130, v130, v73
	v_fmac_f32_e32 v142, v73, v73
	v_add_f32_e32 v196, v196, v130
	v_add_f32_e32 v197, v197, v142
	v_mov_b32_e32 v198, v196
	v_mov_b32_e32 v199, v197
	s_nop 1
	v_permlane16_swap_b32 v198, v196
	v_permlane16_swap_b32 v199, v197
	v_add_f32_e32 v196, v196, v198
	v_add_f32_e32 v197, v197, v199
	v_mov_b32_e32 v198, v196
	v_mov_b32_e32 v199, v197
	s_nop 1
	v_permlane32_swap_b32 v198, v196
	v_permlane32_swap_b32 v199, v197
	v_add_f32_e32 v196, v196, v198
	v_add_f32_e32 v197, v197, v199
	s_mov_b64 exec, 0xffff
	ds_write_b64 v134, v[196:197]
	s_mov_b64 exec, -1
	s_waitcnt lgkmcnt(0)
	s_barrier
; DI unsigned pk2(float lo, float hi) { const f32x2 v = {lo, hi}; const bf16x2_t b = __builtin_convertvector(v, bf16x2_t); return __builtin_bit_cast(unsigned, b); }
; DI size_t xb_off(int tok, int col) { return ((size_t)(((tok >> 7) * 32 + (col >> 5)) * 128 + (tok & 127))) * 32 + (col & 31); }
; DI void unit_O(const Params& p, char* lds, int l, int tile, int glu_tiles, int tile_b) {
;     ...
; #pragma unroll 1
;             for (int i = 0; i < 8; ++i) {
;                 const int pc = (wid * 8 + i + (xrot >> 1)) & 63, kt = pc >> 1, sub = pc & 1;
;                 __builtin_amdgcn_global_load_lds((const unsigned*)(xbres + ((size_t)kt * 128 + half * 32) * 32 + sub * 512 + lane * 8), (unsigned*)(XR + pc * 1024 + lane * 16), 16, 0, 0);
;             }
;     ...
; #pragma unroll
;         for (int mh = 0; mh < 2; ++mh) {
;             const int mt = half * 2 + mh, rl = mh * 16 + l15, row = mt * 16 + l15;
;             float s = 0.f, ss = 0.f;
; #pragma unroll
;             for (int w = 0; w < 4; ++w) { const f32x4 v = *(const f32x4*)&red[rl * 16 + 4 * w]; s += v[0] + v[2]; ss += v[1] + v[3]; }
;             const float mu = s * (1.f / 1024.f);
;             const float var = ss * (1.f / 1024.f) - mu * mu;
;             const float rs = rsqrtf(var + LN_EPS);
;             float* orow = xo + (r0 + row) * 1024 + wid * 128 + quad * 4;
;             bf16_t* brow = xbo + xb_off((int)r0 + row, wid * 128) + quad * 4;
;             const float* gp = GB + wid * 128 + quad * 4;
; #pragma unroll
;             for (int nt = 0; nt < 8; ++nt) {
;                 const f32x4 g = *(const f32x4*)(gp + nt * 16), bb = *(const f32x4*)(gp + 1024 + nt * 16);
;                 f32x4 o;
; #pragma unroll
;                 for (int i = 0; i < 4; ++i) o[i] = (acc[mt][nt][i] - mu) * rs * g[i] + bb[i];
;                 if (l == 0) *(u32x2*)(brow + (nt >> 1) * 4096 + (nt & 1) * 16) = (u32x2){pk2(o[0], o[1]), pk2(o[2], o[3])};
;                 else *(f32x4*)(orow + nt * 16) = o;
;             }
	s_add_u32 s92, s96, 0x800
	s_addc_u32 s93, s97, 0
	s_add_u32 s40, s91, 0x0
	s_mov_b32 m0, s40
	s_nop 0
	global_load_lds_dwordx4 v208, s[92:93]
	s_add_u32 s92, s92, 0x2000
	s_addc_u32 s93, s93, 0
	s_add_u32 m0, m0, 0x400
	s_nop 0
	global_load_lds_dwordx4 v208, s[92:93]
	s_add_u32 s92, s92, 0x2000
	s_addc_u32 s93, s93, 0
	s_add_u32 m0, m0, 0x400
	s_nop 0
	global_load_lds_dwordx4 v208, s[92:93]
	s_add_u32 s92, s92, 0x2000
	s_addc_u32 s93, s93, 0
	s_add_u32 m0, m0, 0x400
	s_nop 0
	global_load_lds_dwordx4 v208, s[92:93]
	ds_read_b128 v[160:163], v135 offset:0
	ds_read_b128 v[164:167], v135 offset:16
	ds_read_b128 v[168:171], v135 offset:32
	ds_read_b128 v[172:175], v135 offset:48
	s_waitcnt lgkmcnt(0)
	v_add_f32_e32 v160, v160, v162
	v_add_f32_e32 v161, v161, v163
	v_add_f32_e32 v164, v164, v166
	v_add_f32_e32 v165, v165, v167
	v_add_f32_e32 v168, v168, v170
	v_add_f32_e32 v169, v169, v171
	v_add_f32_e32 v172, v172, v174
	v_add_f32_e32 v173, v173, v175
	v_add_f32_e32 v160, v160, v164
	v_add_f32_e32 v161, v161, v165
	v_add_f32_e32 v168, v168, v172
	v_add_f32_e32 v169, v169, v173
	v_add_f32_e32 v160, v160, v168
	v_add_f32_e32 v161, v161, v169
	v_mul_f32_e32 v192, 0x3a800000, v160
	v_mul_f32_e32 v193, 0x3a800000, v161
	v_fma_f32 v193, -v192, v192, v193
	v_add_f32_e32 v193, 0x3727c5ac, v193
	v_rsq_f32_e32 v193, v193
	s_nop 0
	s_add_u32 s94, s78, 0x0
	s_addc_u32 s95, s79, 0
	ds_read_b128 v[176:179], v136
	ds_read_b128 v[180:183], v136 offset:4096
	ds_read_b128 v[184:187], v136 offset:64
	ds_read_b128 v[188:191], v136 offset:4160
	s_waitcnt lgkmcnt(2)
	v_sub_f32_e32 v98, v98, v192
	v_mul_f32_e32 v98, v98, v193
	v_fma_f32 v98, v176, v98, v180
	v_sub_f32_e32 v99, v99, v192
	v_mul_f32_e32 v99, v99, v193
	v_fma_f32 v99, v177, v99, v181
	v_sub_f32_e32 v100, v100, v192
	v_mul_f32_e32 v100, v100, v193
	v_fma_f32 v100, v178, v100, v182
	v_sub_f32_e32 v101, v101, v192
	v_mul_f32_e32 v101, v101, v193
	v_fma_f32 v101, v179, v101, v183
	global_store_dwordx4 v137, v[98:101], s[94:95] nt
	ds_read_b128 v[176:179], v136 offset:128
	ds_read_b128 v[180:183], v136 offset:4224
	s_waitcnt lgkmcnt(2)
	v_sub_f32_e32 v94, v94, v192
	v_mul_f32_e32 v94, v94, v193
	v_fma_f32 v94, v184, v94, v188
	v_sub_f32_e32 v95, v95, v192
	v_mul_f32_e32 v95, v95, v193
	v_fma_f32 v95, v185, v95, v189
	v_sub_f32_e32 v96, v96, v192
	v_mul_f32_e32 v96, v96, v193
	v_fma_f32 v96, v186, v96, v190
	v_sub_f32_e32 v97, v97, v192
	v_mul_f32_e32 v97, v97, v193
	v_fma_f32 v97, v187, v97, v191
	global_store_dwordx4 v137, v[94:97], s[94:95] offset:64 nt
	ds_read_b128 v[184:187], v136 offset:192
	ds_read_b128 v[188:191], v136 offset:4288
	s_waitcnt lgkmcnt(2)
	v_sub_f32_e32 v90, v90, v192
	v_mul_f32_e32 v90, v90, v193
	v_fma_f32 v90, v176, v90, v180
	v_sub_f32_e32 v91, v91, v192
	v_mul_f32_e32 v91, v91, v193
	v_fma_f32 v91, v177, v91, v181
	v_sub_f32_e32 v92, v92, v192
	v_mul_f32_e32 v92, v92, v193
	v_fma_f32 v92, v178, v92, v182
	v_sub_f32_e32 v93, v93, v192
	v_mul_f32_e32 v93, v93, v193
	v_fma_f32 v93, v179, v93, v183
	global_store_dwordx4 v137, v[90:93], s[94:95] offset:128 nt
	ds_read_b128 v[176:179], v136 offset:256
	ds_read_b128 v[180:183], v136 offset:4352
	s_waitcnt lgkmcnt(2)
	v_sub_f32_e32 v86, v86, v192
	v_mul_f32_e32 v86, v86, v193
	v_fma_f32 v86, v184, v86, v188
	v_sub_f32_e32 v87, v87, v192
	v_mul_f32_e32 v87, v87, v193
	v_fma_f32 v87, v185, v87, v189
	v_sub_f32_e32 v88, v88, v192
	v_mul_f32_e32 v88, v88, v193
	v_fma_f32 v88, v186, v88, v190
	v_sub_f32_e32 v89, v89, v192
	v_mul_f32_e32 v89, v89, v193
	v_fma_f32 v89, v187, v89, v191
	global_store_dwordx4 v137, v[86:89], s[94:95] offset:192 nt
	ds_read_b128 v[184:187], v136 offset:320
	ds_read_b128 v[188:191], v136 offset:4416
	s_waitcnt lgkmcnt(2)
	v_sub_f32_e32 v82, v82, v192
	v_mul_f32_e32 v82, v82, v193
	v_fma_f32 v82, v176, v82, v180
	v_sub_f32_e32 v83, v83, v192
	v_mul_f32_e32 v83, v83, v193
	v_fma_f32 v83, v177, v83, v181
	v_sub_f32_e32 v84, v84, v192
	v_mul_f32_e32 v84, v84, v193
	v_fma_f32 v84, v178, v84, v182
	v_sub_f32_e32 v85, v85, v192
	v_mul_f32_e32 v85, v85, v193
	v_fma_f32 v85, v179, v85, v183
	global_store_dwordx4 v137, v[82:85], s[94:95] offset:256 nt
	ds_read_b128 v[176:179], v136 offset:384
	ds_read_b128 v[180:183], v136 offset:4480
	s_waitcnt lgkmcnt(2)
	v_sub_f32_e32 v78, v78, v192
	v_mul_f32_e32 v78, v78, v193
	v_fma_f32 v78, v184, v78, v188
	v_sub_f32_e32 v79, v79, v192
	v_mul_f32_e32 v79, v79, v193
	v_fma_f32 v79, v185, v79, v189
	v_sub_f32_e32 v80, v80, v192
	v_mul_f32_e32 v80, v80, v193
	v_fma_f32 v80, v186, v80, v190
	v_sub_f32_e32 v81, v81, v192
	v_mul_f32_e32 v81, v81, v193
	v_fma_f32 v81, v187, v81, v191
	global_store_dwordx4 v137, v[78:81], s[94:95] offset:320 nt
	ds_read_b128 v[184:187], v136 offset:448
	ds_read_b128 v[188:191], v136 offset:4544
	s_waitcnt lgkmcnt(2)
	v_sub_f32_e32 v74, v74, v192
	v_mul_f32_e32 v74, v74, v193
	v_fma_f32 v74, v176, v74, v180
	v_sub_f32_e32 v75, v75, v192
	v_mul_f32_e32 v75, v75, v193
	v_fma_f32 v75, v177, v75, v181
	v_sub_f32_e32 v76, v76, v192
	v_mul_f32_e32 v76, v76, v193
	v_fma_f32 v76, v178, v76, v182
	v_sub_f32_e32 v77, v77, v192
	v_mul_f32_e32 v77, v77, v193
	v_fma_f32 v77, v179, v77, v183
	global_store_dwordx4 v137, v[74:77], s[94:95] offset:384 nt
	s_waitcnt lgkmcnt(0)
	v_sub_f32_e32 v70, v70, v192
	v_mul_f32_e32 v70, v70, v193
	v_fma_f32 v70, v184, v70, v188
	v_sub_f32_e32 v71, v71, v192
	v_mul_f32_e32 v71, v71, v193
	v_fma_f32 v71, v185, v71, v189
	v_sub_f32_e32 v72, v72, v192
	v_mul_f32_e32 v72, v72, v193
	v_fma_f32 v72, v186, v72, v190
	v_sub_f32_e32 v73, v73, v192
	v_mul_f32_e32 v73, v73, v193
	v_fma_f32 v73, v187, v73, v191
	global_store_dwordx4 v137, v[70:73], s[94:95] offset:448 nt
	s_waitcnt vmcnt(12) lgkmcnt(0)
	s_barrier
; DI float bf2f(unsigned b) { return __uint_as_float(b << 16); }
; DI void unit_O(const Params& p, char* lds, int l, int tile, int glu_tiles, int tile_b) {
;     ...
;         float s2[2], ss2[2];
; #pragma unroll
;         for (int mh = 0; mh < 2; ++mh) {
;             const int mt = half * 2 + mh, rl = mh * 16 + l15;
;             float s = 0.f, ss = 0.f;
; #pragma unroll
;             for (int nt = 0; nt < 8; ++nt) {
;                 f32x4 xr;
;                 if (l == 0) {
;                     const int chunk = wid * 32 + nt * 4 + quad;
;                     xr = *(const f32x4*)(XR + rl * 4096 + ((chunk ^ l15) << 4));
;                 } else {
;                     const u32x2 hb = *(const u32x2*)(XR + ((wid * 4 + (nt >> 1)) * 32 + rl) * 64 + (nt & 1) * 32 + quad * 8);
;                     xr = (f32x4){bf2f(hb[0] & 0xffffu), bf2f(hb[0] >> 16), bf2f(hb[1] & 0xffffu), bf2f(hb[1] >> 16)};
;                 }
; #pragma unroll
;                 for (int i = 0; i < 4; ++i) { const float v = acc[mt][nt][i] + DN_ALPHA * xr[i]; acc[mt][nt][i] = v; s += v; ss += v * v; }
;             }
;             s2[mh] = s; ss2[mh] = ss;
;         }
; #pragma unroll
;         for (int mh = 0; mh < 2; ++mh) { s2[mh] += __shfl_xor(s2[mh], 16); ss2[mh] += __shfl_xor(ss2[mh], 16); }
; #pragma unroll
;         for (int mh = 0; mh < 2; ++mh) { s2[mh] += __shfl_xor(s2[mh], 32); ss2[mh] += __shfl_xor(ss2[mh], 32); }
;         if (quad == 0) {
; #pragma unroll
;             for (int mh = 0; mh < 2; ++mh) *(f32x2*)&red[((mh * 16 + l15) * 8 + wid) * 2] = (f32x2){s2[mh], ss2[mh]};
;         }
;         __syncthreads();
	ds_read_b64 v[180:181], v133 offset:32768
	ds_read_b64 v[182:183], v133 offset:32800
	ds_read_b64 v[184:185], v133 offset:33792
	ds_read_b64 v[186:187], v133 offset:33824
	ds_read_b64 v[188:189], v133 offset:34816
	ds_read_b64 v[190:191], v133 offset:34848
	ds_read_b64 v[192:193], v133 offset:35840
	ds_read_b64 v[194:195], v133 offset:35872
	s_waitcnt lgkmcnt(7)
	v_lshlrev_b32_e32 v144, 16, v180
	v_and_b32_e32 v145, 0xffff0000, v180
	v_lshlrev_b32_e32 v146, 16, v181
	v_and_b32_e32 v147, 0xffff0000, v181
	v_fmac_f32_e32 v126, s58, v144
	v_fmac_f32_e32 v127, s58, v145
	v_fmac_f32_e32 v128, s58, v146
	v_fmac_f32_e32 v129, s58, v147
	v_mov_b32_e32 v196, v126
	v_mul_f32_e32 v197, v126, v126
	v_mov_b32_e32 v130, v127
	v_mul_f32_e32 v142, v127, v127
	v_add_f32_e32 v196, v196, v128
	v_fmac_f32_e32 v197, v128, v128
	v_add_f32_e32 v130, v130, v129
	v_fmac_f32_e32 v142, v129, v129
	s_waitcnt lgkmcnt(6)
	v_lshlrev_b32_e32 v148, 16, v182
	v_and_b32_e32 v149, 0xffff0000, v182
	v_lshlrev_b32_e32 v150, 16, v183
	v_and_b32_e32 v151, 0xffff0000, v183
	v_fmac_f32_e32 v122, s58, v148
	v_fmac_f32_e32 v123, s58, v149
	v_fmac_f32_e32 v124, s58, v150
	v_fmac_f32_e32 v125, s58, v151
	v_add_f32_e32 v196, v196, v122
	v_fmac_f32_e32 v197, v122, v122
	v_add_f32_e32 v130, v130, v123
	v_fmac_f32_e32 v142, v123, v123
	v_add_f32_e32 v196, v196, v124
	v_fmac_f32_e32 v197, v124, v124
	v_add_f32_e32 v130, v130, v125
	v_fmac_f32_e32 v142, v125, v125
	s_waitcnt lgkmcnt(5)
	v_lshlrev_b32_e32 v152, 16, v184
	v_and_b32_e32 v153, 0xffff0000, v184
	v_lshlrev_b32_e32 v154, 16, v185
	v_and_b32_e32 v155, 0xffff0000, v185
	v_fmac_f32_e32 v118, s58, v152
	v_fmac_f32_e32 v119, s58, v153
	v_fmac_f32_e32 v120, s58, v154
	v_fmac_f32_e32 v121, s58, v155
	v_add_f32_e32 v196, v196, v118
	v_fmac_f32_e32 v197, v118, v118
	v_add_f32_e32 v130, v130, v119
	v_fmac_f32_e32 v142, v119, v119
	v_add_f32_e32 v196, v196, v120
	v_fmac_f32_e32 v197, v120, v120
	v_add_f32_e32 v130, v130, v121
	v_fmac_f32_e32 v142, v121, v121
	s_waitcnt lgkmcnt(4)
	v_lshlrev_b32_e32 v156, 16, v186
	v_and_b32_e32 v157, 0xffff0000, v186
	v_lshlrev_b32_e32 v158, 16, v187
	v_and_b32_e32 v159, 0xffff0000, v187
	v_fmac_f32_e32 v114, s58, v156
	v_fmac_f32_e32 v115, s58, v157
	v_fmac_f32_e32 v116, s58, v158
	v_fmac_f32_e32 v117, s58, v159
	v_add_f32_e32 v196, v196, v114
	v_fmac_f32_e32 v197, v114, v114
	v_add_f32_e32 v130, v130, v115
	v_fmac_f32_e32 v142, v115, v115
	v_add_f32_e32 v196, v196, v116
	v_fmac_f32_e32 v197, v116, v116
	v_add_f32_e32 v130, v130, v117
	v_fmac_f32_e32 v142, v117, v117
	s_waitcnt lgkmcnt(3)
	v_lshlrev_b32_e32 v160, 16, v188
	v_and_b32_e32 v161, 0xffff0000, v188
	v_lshlrev_b32_e32 v162, 16, v189
	v_and_b32_e32 v163, 0xffff0000, v189
	v_fmac_f32_e32 v110, s58, v160
	v_fmac_f32_e32 v111, s58, v161
	v_fmac_f32_e32 v112, s58, v162
	v_fmac_f32_e32 v113, s58, v163
	v_add_f32_e32 v196, v196, v110
	v_fmac_f32_e32 v197, v110, v110
	v_add_f32_e32 v130, v130, v111
	v_fmac_f32_e32 v142, v111, v111
	v_add_f32_e32 v196, v196, v112
	v_fmac_f32_e32 v197, v112, v112
	v_add_f32_e32 v130, v130, v113
	v_fmac_f32_e32 v142, v113, v113
	s_waitcnt lgkmcnt(2)
	v_lshlrev_b32_e32 v164, 16, v190
	v_and_b32_e32 v165, 0xffff0000, v190
	v_lshlrev_b32_e32 v166, 16, v191
	v_and_b32_e32 v167, 0xffff0000, v191
	v_fmac_f32_e32 v106, s58, v164
	v_fmac_f32_e32 v107, s58, v165
	v_fmac_f32_e32 v108, s58, v166
	v_fmac_f32_e32 v109, s58, v167
	v_add_f32_e32 v196, v196, v106
	v_fmac_f32_e32 v197, v106, v106
	v_add_f32_e32 v130, v130, v107
	v_fmac_f32_e32 v142, v107, v107
	v_add_f32_e32 v196, v196, v108
	v_fmac_f32_e32 v197, v108, v108
	v_add_f32_e32 v130, v130, v109
	v_fmac_f32_e32 v142, v109, v109
	s_waitcnt lgkmcnt(1)
	v_lshlrev_b32_e32 v168, 16, v192
	v_and_b32_e32 v169, 0xffff0000, v192
	v_lshlrev_b32_e32 v170, 16, v193
	v_and_b32_e32 v171, 0xffff0000, v193
	v_fmac_f32_e32 v102, s58, v168
	v_fmac_f32_e32 v103, s58, v169
	v_fmac_f32_e32 v104, s58, v170
	v_fmac_f32_e32 v105, s58, v171
	v_add_f32_e32 v196, v196, v102
	v_fmac_f32_e32 v197, v102, v102
	v_add_f32_e32 v130, v130, v103
	v_fmac_f32_e32 v142, v103, v103
	v_add_f32_e32 v196, v196, v104
	v_fmac_f32_e32 v197, v104, v104
	v_add_f32_e32 v130, v130, v105
	v_fmac_f32_e32 v142, v105, v105
	s_waitcnt lgkmcnt(0)
	v_lshlrev_b32_e32 v172, 16, v194
	v_and_b32_e32 v173, 0xffff0000, v194
	v_lshlrev_b32_e32 v174, 16, v195
	v_and_b32_e32 v175, 0xffff0000, v195
	v_fmac_f32_e32 v66, s58, v172
	v_fmac_f32_e32 v67, s58, v173
	v_fmac_f32_e32 v68, s58, v174
	v_fmac_f32_e32 v69, s58, v175
	v_add_f32_e32 v196, v196, v66
	v_fmac_f32_e32 v197, v66, v66
	v_add_f32_e32 v130, v130, v67
	v_fmac_f32_e32 v142, v67, v67
	v_add_f32_e32 v196, v196, v68
	v_fmac_f32_e32 v197, v68, v68
	v_add_f32_e32 v130, v130, v69
	v_fmac_f32_e32 v142, v69, v69
	v_add_f32_e32 v196, v196, v130
	v_add_f32_e32 v197, v197, v142
	v_mov_b32_e32 v198, v196
	v_mov_b32_e32 v199, v197
	s_nop 1
	v_permlane16_swap_b32 v198, v196
	v_permlane16_swap_b32 v199, v197
	v_add_f32_e32 v196, v196, v198
	v_add_f32_e32 v197, v197, v199
	v_mov_b32_e32 v198, v196
	v_mov_b32_e32 v199, v197
	s_nop 1
	v_permlane32_swap_b32 v198, v196
	v_permlane32_swap_b32 v199, v197
	v_add_f32_e32 v196, v196, v198
	v_add_f32_e32 v197, v197, v199
	s_mov_b64 exec, 0xffff
	ds_write_b64 v134, v[196:197]
	s_mov_b64 exec, -1
	s_waitcnt lgkmcnt(0)
	s_barrier
; DI unsigned pk2(float lo, float hi) { const f32x2 v = {lo, hi}; const bf16x2_t b = __builtin_convertvector(v, bf16x2_t); return __builtin_bit_cast(unsigned, b); }
; DI size_t xb_off(int tok, int col) { return ((size_t)(((tok >> 7) * 32 + (col >> 5)) * 128 + (tok & 127))) * 32 + (col & 31); }
; DI void unit_O(const Params& p, char* lds, int l, int tile, int glu_tiles, int tile_b) {
;     ...
; #pragma unroll 1
;             for (int i = 0; i < 8; ++i) {
;                 const int pc = (wid * 8 + i + (xrot >> 1)) & 63, kt = pc >> 1, sub = pc & 1;
;                 __builtin_amdgcn_global_load_lds((const unsigned*)(xbres + ((size_t)kt * 128 + half * 32) * 32 + sub * 512 + lane * 8), (unsigned*)(XR + pc * 1024 + lane * 16), 16, 0, 0);
;             }
;     ...
; #pragma unroll
;         for (int mh = 0; mh < 2; ++mh) {
;             const int mt = half * 2 + mh, rl = mh * 16 + l15, row = mt * 16 + l15;
;             float s = 0.f, ss = 0.f;
; #pragma unroll
;             for (int w = 0; w < 4; ++w) { const f32x4 v = *(const f32x4*)&red[rl * 16 + 4 * w]; s += v[0] + v[2]; ss += v[1] + v[3]; }
;             const float mu = s * (1.f / 1024.f);
;             const float var = ss * (1.f / 1024.f) - mu * mu;
;             const float rs = rsqrtf(var + LN_EPS);
;             float* orow = xo + (r0 + row) * 1024 + wid * 128 + quad * 4;
;             bf16_t* brow = xbo + xb_off((int)r0 + row, wid * 128) + quad * 4;
;             const float* gp = GB + wid * 128 + quad * 4;
; #pragma unroll
;             for (int nt = 0; nt < 8; ++nt) {
;                 const f32x4 g = *(const f32x4*)(gp + nt * 16), bb = *(const f32x4*)(gp + 1024 + nt * 16);
;                 f32x4 o;
; #pragma unroll
;                 for (int i = 0; i < 4; ++i) o[i] = (acc[mt][nt][i] - mu) * rs * g[i] + bb[i];
;                 if (l == 0) *(u32x2*)(brow + (nt >> 1) * 4096 + (nt & 1) * 16) = (u32x2){pk2(o[0], o[1]), pk2(o[2], o[3])};
;                 else *(f32x4*)(orow + nt * 16) = o;
;             }
	s_add_u32 s92, s96, 0xc00
	s_addc_u32 s93, s97, 0
	s_add_u32 s40, s91, 0x8000
	s_mov_b32 m0, s40
	s_nop 0
	global_load_lds_dwordx4 v208, s[92:93]
	s_add_u32 s92, s92, 0x2000
	s_addc_u32 s93, s93, 0
	s_add_u32 m0, m0, 0x400
	s_nop 0
	global_load_lds_dwordx4 v208, s[92:93]
	s_add_u32 s92, s92, 0x2000
	s_addc_u32 s93, s93, 0
	s_add_u32 m0, m0, 0x400
	s_nop 0
	global_load_lds_dwordx4 v208, s[92:93]
	s_add_u32 s92, s92, 0x2000
	s_addc_u32 s93, s93, 0
	s_add_u32 m0, m0, 0x400
	s_nop 0
	global_load_lds_dwordx4 v208, s[92:93]
	ds_read_b128 v[160:163], v135 offset:0
	ds_read_b128 v[164:167], v135 offset:16
	ds_read_b128 v[168:171], v135 offset:32
	ds_read_b128 v[172:175], v135 offset:48
	s_waitcnt lgkmcnt(0)
	v_add_f32_e32 v160, v160, v162
	v_add_f32_e32 v161, v161, v163
	v_add_f32_e32 v164, v164, v166
	v_add_f32_e32 v165, v165, v167
	v_add_f32_e32 v168, v168, v170
	v_add_f32_e32 v169, v169, v171
	v_add_f32_e32 v172, v172, v174
	v_add_f32_e32 v173, v173, v175
	v_add_f32_e32 v160, v160, v164
	v_add_f32_e32 v161, v161, v165
	v_add_f32_e32 v168, v168, v172
	v_add_f32_e32 v169, v169, v173
	v_add_f32_e32 v160, v160, v168
	v_add_f32_e32 v161, v161, v169
	v_mul_f32_e32 v192, 0x3a800000, v160
	v_mul_f32_e32 v193, 0x3a800000, v161
	v_fma_f32 v193, -v192, v192, v193
	v_add_f32_e32 v193, 0x3727c5ac, v193
	v_rsq_f32_e32 v193, v193
	s_nop 0
	s_add_u32 s94, s78, 0x10000
	s_addc_u32 s95, s79, 0
	ds_read_b128 v[176:179], v136
	ds_read_b128 v[180:183], v136 offset:4096
	ds_read_b128 v[184:187], v136 offset:64
	ds_read_b128 v[188:191], v136 offset:4160
	s_waitcnt lgkmcnt(2)
	v_sub_f32_e32 v126, v126, v192
	v_mul_f32_e32 v126, v126, v193
	v_fma_f32 v126, v176, v126, v180
	v_sub_f32_e32 v127, v127, v192
	v_mul_f32_e32 v127, v127, v193
	v_fma_f32 v127, v177, v127, v181
	v_sub_f32_e32 v128, v128, v192
	v_mul_f32_e32 v128, v128, v193
	v_fma_f32 v128, v178, v128, v182
	v_sub_f32_e32 v129, v129, v192
	v_mul_f32_e32 v129, v129, v193
	v_fma_f32 v129, v179, v129, v183
	global_store_dwordx4 v137, v[126:129], s[94:95] nt
	ds_read_b128 v[176:179], v136 offset:128
	ds_read_b128 v[180:183], v136 offset:4224
	s_waitcnt lgkmcnt(2)
	v_sub_f32_e32 v122, v122, v192
	v_mul_f32_e32 v122, v122, v193
	v_fma_f32 v122, v184, v122, v188
	v_sub_f32_e32 v123, v123, v192
	v_mul_f32_e32 v123, v123, v193
	v_fma_f32 v123, v185, v123, v189
	v_sub_f32_e32 v124, v124, v192
	v_mul_f32_e32 v124, v124, v193
	v_fma_f32 v124, v186, v124, v190
	v_sub_f32_e32 v125, v125, v192
	v_mul_f32_e32 v125, v125, v193
	v_fma_f32 v125, v187, v125, v191
	global_store_dwordx4 v137, v[122:125], s[94:95] offset:64 nt
	ds_read_b128 v[184:187], v136 offset:192
	ds_read_b128 v[188:191], v136 offset:4288
	s_waitcnt lgkmcnt(2)
	v_sub_f32_e32 v118, v118, v192
	v_mul_f32_e32 v118, v118, v193
	v_fma_f32 v118, v176, v118, v180
	v_sub_f32_e32 v119, v119, v192
	v_mul_f32_e32 v119, v119, v193
	v_fma_f32 v119, v177, v119, v181
	v_sub_f32_e32 v120, v120, v192
	v_mul_f32_e32 v120, v120, v193
	v_fma_f32 v120, v178, v120, v182
	v_sub_f32_e32 v121, v121, v192
	v_mul_f32_e32 v121, v121, v193
	v_fma_f32 v121, v179, v121, v183
	global_store_dwordx4 v137, v[118:121], s[94:95] offset:128 nt
	ds_read_b128 v[176:179], v136 offset:256
	ds_read_b128 v[180:183], v136 offset:4352
	s_waitcnt lgkmcnt(2)
	v_sub_f32_e32 v114, v114, v192
	v_mul_f32_e32 v114, v114, v193
	v_fma_f32 v114, v184, v114, v188
	v_sub_f32_e32 v115, v115, v192
	v_mul_f32_e32 v115, v115, v193
	v_fma_f32 v115, v185, v115, v189
	v_sub_f32_e32 v116, v116, v192
	v_mul_f32_e32 v116, v116, v193
	v_fma_f32 v116, v186, v116, v190
	v_sub_f32_e32 v117, v117, v192
	v_mul_f32_e32 v117, v117, v193
	v_fma_f32 v117, v187, v117, v191
	global_store_dwordx4 v137, v[114:117], s[94:95] offset:192 nt
	ds_read_b128 v[184:187], v136 offset:320
	ds_read_b128 v[188:191], v136 offset:4416
	s_waitcnt lgkmcnt(2)
	v_sub_f32_e32 v110, v110, v192
	v_mul_f32_e32 v110, v110, v193
	v_fma_f32 v110, v176, v110, v180
	v_sub_f32_e32 v111, v111, v192
	v_mul_f32_e32 v111, v111, v193
	v_fma_f32 v111, v177, v111, v181
	v_sub_f32_e32 v112, v112, v192
	v_mul_f32_e32 v112, v112, v193
	v_fma_f32 v112, v178, v112, v182
	v_sub_f32_e32 v113, v113, v192
	v_mul_f32_e32 v113, v113, v193
	v_fma_f32 v113, v179, v113, v183
	global_store_dwordx4 v137, v[110:113], s[94:95] offset:256 nt
	ds_read_b128 v[176:179], v136 offset:384
	ds_read_b128 v[180:183], v136 offset:4480
	s_waitcnt lgkmcnt(2)
	v_sub_f32_e32 v106, v106, v192
	v_mul_f32_e32 v106, v106, v193
	v_fma_f32 v106, v184, v106, v188
	v_sub_f32_e32 v107, v107, v192
	v_mul_f32_e32 v107, v107, v193
	v_fma_f32 v107, v185, v107, v189
	v_sub_f32_e32 v108, v108, v192
	v_mul_f32_e32 v108, v108, v193
	v_fma_f32 v108, v186, v108, v190
	v_sub_f32_e32 v109, v109, v192
	v_mul_f32_e32 v109, v109, v193
	v_fma_f32 v109, v187, v109, v191
	global_store_dwordx4 v137, v[106:109], s[94:95] offset:320 nt
	ds_read_b128 v[184:187], v136 offset:448
	ds_read_b128 v[188:191], v136 offset:4544
	s_waitcnt lgkmcnt(2)
	v_sub_f32_e32 v102, v102, v192
	v_mul_f32_e32 v102, v102, v193
	v_fma_f32 v102, v176, v102, v180
	v_sub_f32_e32 v103, v103, v192
	v_mul_f32_e32 v103, v103, v193
	v_fma_f32 v103, v177, v103, v181
	v_sub_f32_e32 v104, v104, v192
	v_mul_f32_e32 v104, v104, v193
	v_fma_f32 v104, v178, v104, v182
	v_sub_f32_e32 v105, v105, v192
	v_mul_f32_e32 v105, v105, v193
	v_fma_f32 v105, v179, v105, v183
	global_store_dwordx4 v137, v[102:105], s[94:95] offset:384 nt
	s_waitcnt lgkmcnt(0)
	v_sub_f32_e32 v66, v66, v192
	v_mul_f32_e32 v66, v66, v193
	v_fma_f32 v66, v184, v66, v188
	v_sub_f32_e32 v67, v67, v192
	v_mul_f32_e32 v67, v67, v193
	v_fma_f32 v67, v185, v67, v189
	v_sub_f32_e32 v68, v68, v192
	v_mul_f32_e32 v68, v68, v193
	v_fma_f32 v68, v186, v68, v190
	v_sub_f32_e32 v69, v69, v192
	v_mul_f32_e32 v69, v69, v193
	v_fma_f32 v69, v187, v69, v191
	global_store_dwordx4 v137, v[66:69], s[94:95] offset:448 nt
	s_waitcnt vmcnt(20) lgkmcnt(0)
	s_barrier
; DI float bf2f(unsigned b) { return __uint_as_float(b << 16); }
; DI void unit_O(const Params& p, char* lds, int l, int tile, int glu_tiles, int tile_b) {
;     ...
;         float s2[2], ss2[2];
; #pragma unroll
;         for (int mh = 0; mh < 2; ++mh) {
;             const int mt = half * 2 + mh, rl = mh * 16 + l15;
;             float s = 0.f, ss = 0.f;
; #pragma unroll
;             for (int nt = 0; nt < 8; ++nt) {
;                 f32x4 xr;
;                 if (l == 0) {
;                     const int chunk = wid * 32 + nt * 4 + quad;
;                     xr = *(const f32x4*)(XR + rl * 4096 + ((chunk ^ l15) << 4));
;                 } else {
;                     const u32x2 hb = *(const u32x2*)(XR + ((wid * 4 + (nt >> 1)) * 32 + rl) * 64 + (nt & 1) * 32 + quad * 8);
;                     xr = (f32x4){bf2f(hb[0] & 0xffffu), bf2f(hb[0] >> 16), bf2f(hb[1] & 0xffffu), bf2f(hb[1] >> 16)};
;                 }
; #pragma unroll
;                 for (int i = 0; i < 4; ++i) { const float v = acc[mt][nt][i] + DN_ALPHA * xr[i]; acc[mt][nt][i] = v; s += v; ss += v * v; }
;             }
;             s2[mh] = s; ss2[mh] = ss;
;         }
; #pragma unroll
;         for (int mh = 0; mh < 2; ++mh) { s2[mh] += __shfl_xor(s2[mh], 16); ss2[mh] += __shfl_xor(ss2[mh], 16); }
; #pragma unroll
;         for (int mh = 0; mh < 2; ++mh) { s2[mh] += __shfl_xor(s2[mh], 32); ss2[mh] += __shfl_xor(ss2[mh], 32); }
;         if (quad == 0) {
; #pragma unroll
;             for (int mh = 0; mh < 2; ++mh) *(f32x2*)&red[((mh * 16 + l15) * 8 + wid) * 2] = (f32x2){s2[mh], ss2[mh]};
;         }
;         __syncthreads();
	ds_read_b64 v[180:181], v133 offset:0
	ds_read_b64 v[182:183], v133 offset:32
	ds_read_b64 v[184:185], v133 offset:1024
	ds_read_b64 v[186:187], v133 offset:1056
	ds_read_b64 v[188:189], v133 offset:2048
	ds_read_b64 v[190:191], v133 offset:2080
	ds_read_b64 v[192:193], v133 offset:3072
	ds_read_b64 v[194:195], v133 offset:3104
	s_waitcnt lgkmcnt(7)
	v_lshlrev_b32_e32 v144, 16, v180
	v_and_b32_e32 v145, 0xffff0000, v180
	v_lshlrev_b32_e32 v146, 16, v181
	v_and_b32_e32 v147, 0xffff0000, v181
	v_fmac_f32_e32 v34, s58, v144
	v_fmac_f32_e32 v35, s58, v145
	v_fmac_f32_e32 v36, s58, v146
	v_fmac_f32_e32 v37, s58, v147
	v_mov_b32_e32 v196, v34
	v_mul_f32_e32 v197, v34, v34
	v_mov_b32_e32 v130, v35
	v_mul_f32_e32 v142, v35, v35
	v_add_f32_e32 v196, v196, v36
	v_fmac_f32_e32 v197, v36, v36
	v_add_f32_e32 v130, v130, v37
	v_fmac_f32_e32 v142, v37, v37
	s_waitcnt lgkmcnt(6)
	v_lshlrev_b32_e32 v148, 16, v182
	v_and_b32_e32 v149, 0xffff0000, v182
	v_lshlrev_b32_e32 v150, 16, v183
	v_and_b32_e32 v151, 0xffff0000, v183
	v_fmac_f32_e32 v30, s58, v148
	v_fmac_f32_e32 v31, s58, v149
	v_fmac_f32_e32 v32, s58, v150
	v_fmac_f32_e32 v33, s58, v151
	v_add_f32_e32 v196, v196, v30
	v_fmac_f32_e32 v197, v30, v30
	v_add_f32_e32 v130, v130, v31
	v_fmac_f32_e32 v142, v31, v31
	v_add_f32_e32 v196, v196, v32
	v_fmac_f32_e32 v197, v32, v32
	v_add_f32_e32 v130, v130, v33
	v_fmac_f32_e32 v142, v33, v33
	s_waitcnt lgkmcnt(5)
	v_lshlrev_b32_e32 v152, 16, v184
	v_and_b32_e32 v153, 0xffff0000, v184
	v_lshlrev_b32_e32 v154, 16, v185
	v_and_b32_e32 v155, 0xffff0000, v185
	v_fmac_f32_e32 v26, s58, v152
	v_fmac_f32_e32 v27, s58, v153
	v_fmac_f32_e32 v28, s58, v154
	v_fmac_f32_e32 v29, s58, v155
	v_add_f32_e32 v196, v196, v26
	v_fmac_f32_e32 v197, v26, v26
	v_add_f32_e32 v130, v130, v27
	v_fmac_f32_e32 v142, v27, v27
	v_add_f32_e32 v196, v196, v28
	v_fmac_f32_e32 v197, v28, v28
	v_add_f32_e32 v130, v130, v29
	v_fmac_f32_e32 v142, v29, v29
	s_waitcnt lgkmcnt(4)
	v_lshlrev_b32_e32 v156, 16, v186
	v_and_b32_e32 v157, 0xffff0000, v186
	v_lshlrev_b32_e32 v158, 16, v187
	v_and_b32_e32 v159, 0xffff0000, v187
	v_fmac_f32_e32 v22, s58, v156
	v_fmac_f32_e32 v23, s58, v157
	v_fmac_f32_e32 v24, s58, v158
	v_fmac_f32_e32 v25, s58, v159
	v_add_f32_e32 v196, v196, v22
	v_fmac_f32_e32 v197, v22, v22
	v_add_f32_e32 v130, v130, v23
	v_fmac_f32_e32 v142, v23, v23
	v_add_f32_e32 v196, v196, v24
	v_fmac_f32_e32 v197, v24, v24
	v_add_f32_e32 v130, v130, v25
	v_fmac_f32_e32 v142, v25, v25
	s_waitcnt lgkmcnt(3)
	v_lshlrev_b32_e32 v160, 16, v188
	v_and_b32_e32 v161, 0xffff0000, v188
	v_lshlrev_b32_e32 v162, 16, v189
	v_and_b32_e32 v163, 0xffff0000, v189
	v_fmac_f32_e32 v18, s58, v160
	v_fmac_f32_e32 v19, s58, v161
	v_fmac_f32_e32 v20, s58, v162
	v_fmac_f32_e32 v21, s58, v163
	v_add_f32_e32 v196, v196, v18
	v_fmac_f32_e32 v197, v18, v18
	v_add_f32_e32 v130, v130, v19
	v_fmac_f32_e32 v142, v19, v19
	v_add_f32_e32 v196, v196, v20
	v_fmac_f32_e32 v197, v20, v20
	v_add_f32_e32 v130, v130, v21
	v_fmac_f32_e32 v142, v21, v21
	s_waitcnt lgkmcnt(2)
	v_lshlrev_b32_e32 v164, 16, v190
	v_and_b32_e32 v165, 0xffff0000, v190
	v_lshlrev_b32_e32 v166, 16, v191
	v_and_b32_e32 v167, 0xffff0000, v191
	v_fmac_f32_e32 v14, s58, v164
	v_fmac_f32_e32 v15, s58, v165
	v_fmac_f32_e32 v16, s58, v166
	v_fmac_f32_e32 v17, s58, v167
	v_add_f32_e32 v196, v196, v14
	v_fmac_f32_e32 v197, v14, v14
	v_add_f32_e32 v130, v130, v15
	v_fmac_f32_e32 v142, v15, v15
	v_add_f32_e32 v196, v196, v16
	v_fmac_f32_e32 v197, v16, v16
	v_add_f32_e32 v130, v130, v17
	v_fmac_f32_e32 v142, v17, v17
	s_waitcnt lgkmcnt(1)
	v_lshlrev_b32_e32 v168, 16, v192
	v_and_b32_e32 v169, 0xffff0000, v192
	v_lshlrev_b32_e32 v170, 16, v193
	v_and_b32_e32 v171, 0xffff0000, v193
	v_fmac_f32_e32 v10, s58, v168
	v_fmac_f32_e32 v11, s58, v169
	v_fmac_f32_e32 v12, s58, v170
	v_fmac_f32_e32 v13, s58, v171
	v_add_f32_e32 v196, v196, v10
	v_fmac_f32_e32 v197, v10, v10
	v_add_f32_e32 v130, v130, v11
	v_fmac_f32_e32 v142, v11, v11
	v_add_f32_e32 v196, v196, v12
	v_fmac_f32_e32 v197, v12, v12
	v_add_f32_e32 v130, v130, v13
	v_fmac_f32_e32 v142, v13, v13
	s_waitcnt lgkmcnt(0)
	v_lshlrev_b32_e32 v172, 16, v194
	v_and_b32_e32 v173, 0xffff0000, v194
	v_lshlrev_b32_e32 v174, 16, v195
	v_and_b32_e32 v175, 0xffff0000, v195
	v_fmac_f32_e32 v6, s58, v172
	v_fmac_f32_e32 v7, s58, v173
	v_fmac_f32_e32 v8, s58, v174
	v_fmac_f32_e32 v9, s58, v175
	v_add_f32_e32 v196, v196, v6
	v_fmac_f32_e32 v197, v6, v6
	v_add_f32_e32 v130, v130, v7
	v_fmac_f32_e32 v142, v7, v7
	v_add_f32_e32 v196, v196, v8
	v_fmac_f32_e32 v197, v8, v8
	v_add_f32_e32 v130, v130, v9
	v_fmac_f32_e32 v142, v9, v9
	v_add_f32_e32 v196, v196, v130
	v_add_f32_e32 v197, v197, v142
	v_mov_b32_e32 v198, v196
	v_mov_b32_e32 v199, v197
	s_nop 1
	v_permlane16_swap_b32 v198, v196
	v_permlane16_swap_b32 v199, v197
	v_add_f32_e32 v196, v196, v198
	v_add_f32_e32 v197, v197, v199
	v_mov_b32_e32 v198, v196
	v_mov_b32_e32 v199, v197
	s_nop 1
	v_permlane32_swap_b32 v198, v196
	v_permlane32_swap_b32 v199, v197
	v_add_f32_e32 v196, v196, v198
	v_add_f32_e32 v197, v197, v199
	s_mov_b64 exec, 0xffff
	ds_write_b64 v134, v[196:197]
	s_mov_b64 exec, -1
	s_waitcnt lgkmcnt(0)
	s_barrier
; DI unsigned pk2(float lo, float hi) { const f32x2 v = {lo, hi}; const bf16x2_t b = __builtin_convertvector(v, bf16x2_t); return __builtin_bit_cast(unsigned, b); }
; DI size_t xb_off(int tok, int col) { return ((size_t)(((tok >> 7) * 32 + (col >> 5)) * 128 + (tok & 127))) * 32 + (col & 31); }
; DI void unit_O(const Params& p, char* lds, int l, int tile, int glu_tiles, int tile_b) {
;     ...
; #pragma unroll
;         for (int mh = 0; mh < 2; ++mh) {
;             const int mt = half * 2 + mh, rl = mh * 16 + l15, row = mt * 16 + l15;
;             float s = 0.f, ss = 0.f;
; #pragma unroll
;             for (int w = 0; w < 4; ++w) { const f32x4 v = *(const f32x4*)&red[rl * 16 + 4 * w]; s += v[0] + v[2]; ss += v[1] + v[3]; }
;             const float mu = s * (1.f / 1024.f);
;             const float var = ss * (1.f / 1024.f) - mu * mu;
;             const float rs = rsqrtf(var + LN_EPS);
;             float* orow = xo + (r0 + row) * 1024 + wid * 128 + quad * 4;
;             bf16_t* brow = xbo + xb_off((int)r0 + row, wid * 128) + quad * 4;
;             const float* gp = GB + wid * 128 + quad * 4;
; #pragma unroll
;             for (int nt = 0; nt < 8; ++nt) {
;                 const f32x4 g = *(const f32x4*)(gp + nt * 16), bb = *(const f32x4*)(gp + 1024 + nt * 16);
;                 f32x4 o;
; #pragma unroll
;                 for (int i = 0; i < 4; ++i) o[i] = (acc[mt][nt][i] - mu) * rs * g[i] + bb[i];
;                 if (l == 0) *(u32x2*)(brow + (nt >> 1) * 4096 + (nt & 1) * 16) = (u32x2){pk2(o[0], o[1]), pk2(o[2], o[3])};
;                 else *(f32x4*)(orow + nt * 16) = o;
;             }
	ds_read_b128 v[160:163], v135 offset:0
	ds_read_b128 v[164:167], v135 offset:16
	ds_read_b128 v[168:171], v135 offset:32
	ds_read_b128 v[172:175], v135 offset:48
	s_waitcnt lgkmcnt(0)
	v_add_f32_e32 v160, v160, v162
	v_add_f32_e32 v161, v161, v163
	v_add_f32_e32 v164, v164, v166
	v_add_f32_e32 v165, v165, v167
	v_add_f32_e32 v168, v168, v170
	v_add_f32_e32 v169, v169, v171
	v_add_f32_e32 v172, v172, v174
	v_add_f32_e32 v173, v173, v175
	v_add_f32_e32 v160, v160, v164
	v_add_f32_e32 v161, v161, v165
	v_add_f32_e32 v168, v168, v172
	v_add_f32_e32 v169, v169, v173
	v_add_f32_e32 v160, v160, v168
	v_add_f32_e32 v161, v161, v169
	v_mul_f32_e32 v192, 0x3a800000, v160
	v_mul_f32_e32 v193, 0x3a800000, v161
	v_fma_f32 v193, -v192, v192, v193
	v_add_f32_e32 v193, 0x3727c5ac, v193
	v_rsq_f32_e32 v193, v193
	s_nop 0
	s_add_u32 s94, s78, 0x20000
	s_addc_u32 s95, s79, 0
	ds_read_b128 v[176:179], v136
	ds_read_b128 v[180:183], v136 offset:4096
	ds_read_b128 v[184:187], v136 offset:64
	ds_read_b128 v[188:191], v136 offset:4160
	s_waitcnt lgkmcnt(2)
	v_sub_f32_e32 v34, v34, v192
	v_mul_f32_e32 v34, v34, v193
	v_fma_f32 v34, v176, v34, v180
	v_sub_f32_e32 v35, v35, v192
	v_mul_f32_e32 v35, v35, v193
	v_fma_f32 v35, v177, v35, v181
	v_sub_f32_e32 v36, v36, v192
	v_mul_f32_e32 v36, v36, v193
	v_fma_f32 v36, v178, v36, v182
	v_sub_f32_e32 v37, v37, v192
	v_mul_f32_e32 v37, v37, v193
	v_fma_f32 v37, v179, v37, v183
	global_store_dwordx4 v137, v[34:37], s[94:95] nt
	ds_read_b128 v[176:179], v136 offset:128
	ds_read_b128 v[180:183], v136 offset:4224
	s_waitcnt lgkmcnt(2)
	v_sub_f32_e32 v30, v30, v192
	v_mul_f32_e32 v30, v30, v193
	v_fma_f32 v30, v184, v30, v188
	v_sub_f32_e32 v31, v31, v192
	v_mul_f32_e32 v31, v31, v193
	v_fma_f32 v31, v185, v31, v189
	v_sub_f32_e32 v32, v32, v192
	v_mul_f32_e32 v32, v32, v193
	v_fma_f32 v32, v186, v32, v190
	v_sub_f32_e32 v33, v33, v192
	v_mul_f32_e32 v33, v33, v193
	v_fma_f32 v33, v187, v33, v191
	global_store_dwordx4 v137, v[30:33], s[94:95] offset:64 nt
	ds_read_b128 v[184:187], v136 offset:192
	ds_read_b128 v[188:191], v136 offset:4288
	s_waitcnt lgkmcnt(2)
	v_sub_f32_e32 v26, v26, v192
	v_mul_f32_e32 v26, v26, v193
	v_fma_f32 v26, v176, v26, v180
	v_sub_f32_e32 v27, v27, v192
	v_mul_f32_e32 v27, v27, v193
	v_fma_f32 v27, v177, v27, v181
	v_sub_f32_e32 v28, v28, v192
	v_mul_f32_e32 v28, v28, v193
	v_fma_f32 v28, v178, v28, v182
	v_sub_f32_e32 v29, v29, v192
	v_mul_f32_e32 v29, v29, v193
	v_fma_f32 v29, v179, v29, v183
	global_store_dwordx4 v137, v[26:29], s[94:95] offset:128 nt
	ds_read_b128 v[176:179], v136 offset:256
	ds_read_b128 v[180:183], v136 offset:4352
	s_waitcnt lgkmcnt(2)
	v_sub_f32_e32 v22, v22, v192
	v_mul_f32_e32 v22, v22, v193
	v_fma_f32 v22, v184, v22, v188
	v_sub_f32_e32 v23, v23, v192
	v_mul_f32_e32 v23, v23, v193
	v_fma_f32 v23, v185, v23, v189
	v_sub_f32_e32 v24, v24, v192
	v_mul_f32_e32 v24, v24, v193
	v_fma_f32 v24, v186, v24, v190
	v_sub_f32_e32 v25, v25, v192
	v_mul_f32_e32 v25, v25, v193
	v_fma_f32 v25, v187, v25, v191
	global_store_dwordx4 v137, v[22:25], s[94:95] offset:192 nt
	ds_read_b128 v[184:187], v136 offset:320
	ds_read_b128 v[188:191], v136 offset:4416
	s_waitcnt lgkmcnt(2)
	v_sub_f32_e32 v18, v18, v192
	v_mul_f32_e32 v18, v18, v193
	v_fma_f32 v18, v176, v18, v180
	v_sub_f32_e32 v19, v19, v192
	v_mul_f32_e32 v19, v19, v193
	v_fma_f32 v19, v177, v19, v181
	v_sub_f32_e32 v20, v20, v192
	v_mul_f32_e32 v20, v20, v193
	v_fma_f32 v20, v178, v20, v182
	v_sub_f32_e32 v21, v21, v192
	v_mul_f32_e32 v21, v21, v193
	v_fma_f32 v21, v179, v21, v183
	global_store_dwordx4 v137, v[18:21], s[94:95] offset:256 nt
	ds_read_b128 v[176:179], v136 offset:384
	ds_read_b128 v[180:183], v136 offset:4480
	s_waitcnt lgkmcnt(2)
	v_sub_f32_e32 v14, v14, v192
	v_mul_f32_e32 v14, v14, v193
	v_fma_f32 v14, v184, v14, v188
	v_sub_f32_e32 v15, v15, v192
	v_mul_f32_e32 v15, v15, v193
	v_fma_f32 v15, v185, v15, v189
	v_sub_f32_e32 v16, v16, v192
	v_mul_f32_e32 v16, v16, v193
	v_fma_f32 v16, v186, v16, v190
	v_sub_f32_e32 v17, v17, v192
	v_mul_f32_e32 v17, v17, v193
	v_fma_f32 v17, v187, v17, v191
	global_store_dwordx4 v137, v[14:17], s[94:95] offset:320 nt
	ds_read_b128 v[184:187], v136 offset:448
	ds_read_b128 v[188:191], v136 offset:4544
	s_waitcnt lgkmcnt(2)
	v_sub_f32_e32 v10, v10, v192
	v_mul_f32_e32 v10, v10, v193
	v_fma_f32 v10, v176, v10, v180
	v_sub_f32_e32 v11, v11, v192
	v_mul_f32_e32 v11, v11, v193
	v_fma_f32 v11, v177, v11, v181
	v_sub_f32_e32 v12, v12, v192
	v_mul_f32_e32 v12, v12, v193
	v_fma_f32 v12, v178, v12, v182
	v_sub_f32_e32 v13, v13, v192
	v_mul_f32_e32 v13, v13, v193
	v_fma_f32 v13, v179, v13, v183
	global_store_dwordx4 v137, v[10:13], s[94:95] offset:384 nt
	s_waitcnt lgkmcnt(0)
	v_sub_f32_e32 v6, v6, v192
	v_mul_f32_e32 v6, v6, v193
	v_fma_f32 v6, v184, v6, v188
	v_sub_f32_e32 v7, v7, v192
	v_mul_f32_e32 v7, v7, v193
	v_fma_f32 v7, v185, v7, v189
	v_sub_f32_e32 v8, v8, v192
	v_mul_f32_e32 v8, v8, v193
	v_fma_f32 v8, v186, v8, v190
	v_sub_f32_e32 v9, v9, v192
	v_mul_f32_e32 v9, v9, v193
	v_fma_f32 v9, v187, v9, v191
	global_store_dwordx4 v137, v[6:9], s[94:95] offset:448 nt
	s_waitcnt vmcnt(16) lgkmcnt(0)
	s_barrier
; DI float bf2f(unsigned b) { return __uint_as_float(b << 16); }
; DI void unit_O(const Params& p, char* lds, int l, int tile, int glu_tiles, int tile_b) {
;     ...
;         float s2[2], ss2[2];
; #pragma unroll
;         for (int mh = 0; mh < 2; ++mh) {
;             const int mt = half * 2 + mh, rl = mh * 16 + l15;
;             float s = 0.f, ss = 0.f;
; #pragma unroll
;             for (int nt = 0; nt < 8; ++nt) {
;                 f32x4 xr;
;                 if (l == 0) {
;                     const int chunk = wid * 32 + nt * 4 + quad;
;                     xr = *(const f32x4*)(XR + rl * 4096 + ((chunk ^ l15) << 4));
;                 } else {
;                     const u32x2 hb = *(const u32x2*)(XR + ((wid * 4 + (nt >> 1)) * 32 + rl) * 64 + (nt & 1) * 32 + quad * 8);
;                     xr = (f32x4){bf2f(hb[0] & 0xffffu), bf2f(hb[0] >> 16), bf2f(hb[1] & 0xffffu), bf2f(hb[1] >> 16)};
;                 }
; #pragma unroll
;                 for (int i = 0; i < 4; ++i) { const float v = acc[mt][nt][i] + DN_ALPHA * xr[i]; acc[mt][nt][i] = v; s += v; ss += v * v; }
;             }
;             s2[mh] = s; ss2[mh] = ss;
;         }
; #pragma unroll
;         for (int mh = 0; mh < 2; ++mh) { s2[mh] += __shfl_xor(s2[mh], 16); ss2[mh] += __shfl_xor(ss2[mh], 16); }
; #pragma unroll
;         for (int mh = 0; mh < 2; ++mh) { s2[mh] += __shfl_xor(s2[mh], 32); ss2[mh] += __shfl_xor(ss2[mh], 32); }
;         if (quad == 0) {
; #pragma unroll
;             for (int mh = 0; mh < 2; ++mh) *(f32x2*)&red[((mh * 16 + l15) * 8 + wid) * 2] = (f32x2){s2[mh], ss2[mh]};
;         }
;         __syncthreads();
	ds_read_b64 v[180:181], v133 offset:32768
	ds_read_b64 v[182:183], v133 offset:32800
	ds_read_b64 v[184:185], v133 offset:33792
	ds_read_b64 v[186:187], v133 offset:33824
	ds_read_b64 v[188:189], v133 offset:34816
	ds_read_b64 v[190:191], v133 offset:34848
	ds_read_b64 v[192:193], v133 offset:35840
	ds_read_b64 v[194:195], v133 offset:35872
	s_waitcnt lgkmcnt(7)
	v_lshlrev_b32_e32 v144, 16, v180
	v_and_b32_e32 v145, 0xffff0000, v180
	v_lshlrev_b32_e32 v146, 16, v181
	v_and_b32_e32 v147, 0xffff0000, v181
	v_fmac_f32_e32 v62, s58, v144
	v_fmac_f32_e32 v63, s58, v145
	v_fmac_f32_e32 v64, s58, v146
	v_fmac_f32_e32 v65, s58, v147
	v_mov_b32_e32 v196, v62
	v_mul_f32_e32 v197, v62, v62
	v_mov_b32_e32 v130, v63
	v_mul_f32_e32 v142, v63, v63
	v_add_f32_e32 v196, v196, v64
	v_fmac_f32_e32 v197, v64, v64
	v_add_f32_e32 v130, v130, v65
	v_fmac_f32_e32 v142, v65, v65
	s_waitcnt lgkmcnt(6)
	v_lshlrev_b32_e32 v148, 16, v182
	v_and_b32_e32 v149, 0xffff0000, v182
	v_lshlrev_b32_e32 v150, 16, v183
	v_and_b32_e32 v151, 0xffff0000, v183
	v_fmac_f32_e32 v58, s58, v148
	v_fmac_f32_e32 v59, s58, v149
	v_fmac_f32_e32 v60, s58, v150
	v_fmac_f32_e32 v61, s58, v151
	v_add_f32_e32 v196, v196, v58
	v_fmac_f32_e32 v197, v58, v58
	v_add_f32_e32 v130, v130, v59
	v_fmac_f32_e32 v142, v59, v59
	v_add_f32_e32 v196, v196, v60
	v_fmac_f32_e32 v197, v60, v60
	v_add_f32_e32 v130, v130, v61
	v_fmac_f32_e32 v142, v61, v61
	s_waitcnt lgkmcnt(5)
	v_lshlrev_b32_e32 v152, 16, v184
	v_and_b32_e32 v153, 0xffff0000, v184
	v_lshlrev_b32_e32 v154, 16, v185
	v_and_b32_e32 v155, 0xffff0000, v185
	v_fmac_f32_e32 v54, s58, v152
	v_fmac_f32_e32 v55, s58, v153
	v_fmac_f32_e32 v56, s58, v154
	v_fmac_f32_e32 v57, s58, v155
	v_add_f32_e32 v196, v196, v54
	v_fmac_f32_e32 v197, v54, v54
	v_add_f32_e32 v130, v130, v55
	v_fmac_f32_e32 v142, v55, v55
	v_add_f32_e32 v196, v196, v56
	v_fmac_f32_e32 v197, v56, v56
	v_add_f32_e32 v130, v130, v57
	v_fmac_f32_e32 v142, v57, v57
	s_waitcnt lgkmcnt(4)
	v_lshlrev_b32_e32 v156, 16, v186
	v_and_b32_e32 v157, 0xffff0000, v186
	v_lshlrev_b32_e32 v158, 16, v187
	v_and_b32_e32 v159, 0xffff0000, v187
	v_fmac_f32_e32 v50, s58, v156
	v_fmac_f32_e32 v51, s58, v157
	v_fmac_f32_e32 v52, s58, v158
	v_fmac_f32_e32 v53, s58, v159
	v_add_f32_e32 v196, v196, v50
	v_fmac_f32_e32 v197, v50, v50
	v_add_f32_e32 v130, v130, v51
	v_fmac_f32_e32 v142, v51, v51
	v_add_f32_e32 v196, v196, v52
	v_fmac_f32_e32 v197, v52, v52
	v_add_f32_e32 v130, v130, v53
	v_fmac_f32_e32 v142, v53, v53
	s_waitcnt lgkmcnt(3)
	v_lshlrev_b32_e32 v160, 16, v188
	v_and_b32_e32 v161, 0xffff0000, v188
	v_lshlrev_b32_e32 v162, 16, v189
	v_and_b32_e32 v163, 0xffff0000, v189
	v_fmac_f32_e32 v46, s58, v160
	v_fmac_f32_e32 v47, s58, v161
	v_fmac_f32_e32 v48, s58, v162
	v_fmac_f32_e32 v49, s58, v163
	v_add_f32_e32 v196, v196, v46
	v_fmac_f32_e32 v197, v46, v46
	v_add_f32_e32 v130, v130, v47
	v_fmac_f32_e32 v142, v47, v47
	v_add_f32_e32 v196, v196, v48
	v_fmac_f32_e32 v197, v48, v48
	v_add_f32_e32 v130, v130, v49
	v_fmac_f32_e32 v142, v49, v49
	s_waitcnt lgkmcnt(2)
	v_lshlrev_b32_e32 v164, 16, v190
	v_and_b32_e32 v165, 0xffff0000, v190
	v_lshlrev_b32_e32 v166, 16, v191
	v_and_b32_e32 v167, 0xffff0000, v191
	v_fmac_f32_e32 v42, s58, v164
	v_fmac_f32_e32 v43, s58, v165
	v_fmac_f32_e32 v44, s58, v166
	v_fmac_f32_e32 v45, s58, v167
	v_add_f32_e32 v196, v196, v42
	v_fmac_f32_e32 v197, v42, v42
	v_add_f32_e32 v130, v130, v43
	v_fmac_f32_e32 v142, v43, v43
	v_add_f32_e32 v196, v196, v44
	v_fmac_f32_e32 v197, v44, v44
	v_add_f32_e32 v130, v130, v45
	v_fmac_f32_e32 v142, v45, v45
	s_waitcnt lgkmcnt(1)
	v_lshlrev_b32_e32 v168, 16, v192
	v_and_b32_e32 v169, 0xffff0000, v192
	v_lshlrev_b32_e32 v170, 16, v193
	v_and_b32_e32 v171, 0xffff0000, v193
	v_fmac_f32_e32 v38, s58, v168
	v_fmac_f32_e32 v39, s58, v169
	v_fmac_f32_e32 v40, s58, v170
	v_fmac_f32_e32 v41, s58, v171
	v_add_f32_e32 v196, v196, v38
	v_fmac_f32_e32 v197, v38, v38
	v_add_f32_e32 v130, v130, v39
	v_fmac_f32_e32 v142, v39, v39
	v_add_f32_e32 v196, v196, v40
	v_fmac_f32_e32 v197, v40, v40
	v_add_f32_e32 v130, v130, v41
	v_fmac_f32_e32 v142, v41, v41
	s_waitcnt lgkmcnt(0)
	v_lshlrev_b32_e32 v172, 16, v194
	v_and_b32_e32 v173, 0xffff0000, v194
	v_lshlrev_b32_e32 v174, 16, v195
	v_and_b32_e32 v175, 0xffff0000, v195
	v_fmac_f32_e32 v2, s58, v172
	v_fmac_f32_e32 v3, s58, v173
	v_fmac_f32_e32 v4, s58, v174
	v_fmac_f32_e32 v5, s58, v175
	v_add_f32_e32 v196, v196, v2
	v_fmac_f32_e32 v197, v2, v2
	v_add_f32_e32 v130, v130, v3
	v_fmac_f32_e32 v142, v3, v3
	v_add_f32_e32 v196, v196, v4
	v_fmac_f32_e32 v197, v4, v4
	v_add_f32_e32 v130, v130, v5
	v_fmac_f32_e32 v142, v5, v5
	v_add_f32_e32 v196, v196, v130
	v_add_f32_e32 v197, v197, v142
	v_mov_b32_e32 v198, v196
	v_mov_b32_e32 v199, v197
	s_nop 1
	v_permlane16_swap_b32 v198, v196
	v_permlane16_swap_b32 v199, v197
	v_add_f32_e32 v196, v196, v198
	v_add_f32_e32 v197, v197, v199
	v_mov_b32_e32 v198, v196
	v_mov_b32_e32 v199, v197
	s_nop 1
	v_permlane32_swap_b32 v198, v196
	v_permlane32_swap_b32 v199, v197
	v_add_f32_e32 v196, v196, v198
	v_add_f32_e32 v197, v197, v199
	s_mov_b64 exec, 0xffff
	ds_write_b64 v134, v[196:197]
	s_mov_b64 exec, -1
	s_waitcnt lgkmcnt(0)
	s_barrier
; DI unsigned pk2(float lo, float hi) { const f32x2 v = {lo, hi}; const bf16x2_t b = __builtin_convertvector(v, bf16x2_t); return __builtin_bit_cast(unsigned, b); }
; DI size_t xb_off(int tok, int col) { return ((size_t)(((tok >> 7) * 32 + (col >> 5)) * 128 + (tok & 127))) * 32 + (col & 31); }
; DI void unit_O(const Params& p, char* lds, int l, int tile, int glu_tiles, int tile_b) {
;     ...
; #pragma unroll
;         for (int mh = 0; mh < 2; ++mh) {
;             const int mt = half * 2 + mh, rl = mh * 16 + l15, row = mt * 16 + l15;
;             float s = 0.f, ss = 0.f;
; #pragma unroll
;             for (int w = 0; w < 4; ++w) { const f32x4 v = *(const f32x4*)&red[rl * 16 + 4 * w]; s += v[0] + v[2]; ss += v[1] + v[3]; }
;             const float mu = s * (1.f / 1024.f);
;             const float var = ss * (1.f / 1024.f) - mu * mu;
;             const float rs = rsqrtf(var + LN_EPS);
;             float* orow = xo + (r0 + row) * 1024 + wid * 128 + quad * 4;
;             bf16_t* brow = xbo + xb_off((int)r0 + row, wid * 128) + quad * 4;
;             const float* gp = GB + wid * 128 + quad * 4;
; #pragma unroll
;             for (int nt = 0; nt < 8; ++nt) {
;                 const f32x4 g = *(const f32x4*)(gp + nt * 16), bb = *(const f32x4*)(gp + 1024 + nt * 16);
;                 f32x4 o;
; #pragma unroll
;                 for (int i = 0; i < 4; ++i) o[i] = (acc[mt][nt][i] - mu) * rs * g[i] + bb[i];
;                 if (l == 0) *(u32x2*)(brow + (nt >> 1) * 4096 + (nt & 1) * 16) = (u32x2){pk2(o[0], o[1]), pk2(o[2], o[3])};
;                 else *(f32x4*)(orow + nt * 16) = o;
;             }
	ds_read_b128 v[160:163], v135 offset:0
	ds_read_b128 v[164:167], v135 offset:16
	ds_read_b128 v[168:171], v135 offset:32
	ds_read_b128 v[172:175], v135 offset:48
	s_waitcnt lgkmcnt(0)
	v_add_f32_e32 v160, v160, v162
	v_add_f32_e32 v161, v161, v163
	v_add_f32_e32 v164, v164, v166
	v_add_f32_e32 v165, v165, v167
	v_add_f32_e32 v168, v168, v170
	v_add_f32_e32 v169, v169, v171
	v_add_f32_e32 v172, v172, v174
	v_add_f32_e32 v173, v173, v175
	v_add_f32_e32 v160, v160, v164
	v_add_f32_e32 v161, v161, v165
	v_add_f32_e32 v168, v168, v172
	v_add_f32_e32 v169, v169, v173
	v_add_f32_e32 v160, v160, v168
	v_add_f32_e32 v161, v161, v169
	v_mul_f32_e32 v192, 0x3a800000, v160
	v_mul_f32_e32 v193, 0x3a800000, v161
	v_fma_f32 v193, -v192, v192, v193
	v_add_f32_e32 v193, 0x3727c5ac, v193
	v_rsq_f32_e32 v193, v193
	s_nop 0
	s_add_u32 s94, s78, 0x30000
	s_addc_u32 s95, s79, 0
	ds_read_b128 v[176:179], v136
	ds_read_b128 v[180:183], v136 offset:4096
	ds_read_b128 v[184:187], v136 offset:64
	ds_read_b128 v[188:191], v136 offset:4160
	s_waitcnt lgkmcnt(2)
	v_sub_f32_e32 v62, v62, v192
	v_mul_f32_e32 v62, v62, v193
	v_fma_f32 v62, v176, v62, v180
	v_sub_f32_e32 v63, v63, v192
	v_mul_f32_e32 v63, v63, v193
	v_fma_f32 v63, v177, v63, v181
	v_sub_f32_e32 v64, v64, v192
	v_mul_f32_e32 v64, v64, v193
	v_fma_f32 v64, v178, v64, v182
	v_sub_f32_e32 v65, v65, v192
	v_mul_f32_e32 v65, v65, v193
	v_fma_f32 v65, v179, v65, v183
	global_store_dwordx4 v137, v[62:65], s[94:95] nt
	ds_read_b128 v[176:179], v136 offset:128
	ds_read_b128 v[180:183], v136 offset:4224
	s_waitcnt lgkmcnt(2)
	v_sub_f32_e32 v58, v58, v192
	v_mul_f32_e32 v58, v58, v193
	v_fma_f32 v58, v184, v58, v188
	v_sub_f32_e32 v59, v59, v192
	v_mul_f32_e32 v59, v59, v193
	v_fma_f32 v59, v185, v59, v189
	v_sub_f32_e32 v60, v60, v192
	v_mul_f32_e32 v60, v60, v193
	v_fma_f32 v60, v186, v60, v190
	v_sub_f32_e32 v61, v61, v192
	v_mul_f32_e32 v61, v61, v193
	v_fma_f32 v61, v187, v61, v191
	global_store_dwordx4 v137, v[58:61], s[94:95] offset:64 nt
	ds_read_b128 v[184:187], v136 offset:192
	ds_read_b128 v[188:191], v136 offset:4288
	s_waitcnt lgkmcnt(2)
	v_sub_f32_e32 v54, v54, v192
	v_mul_f32_e32 v54, v54, v193
	v_fma_f32 v54, v176, v54, v180
	v_sub_f32_e32 v55, v55, v192
	v_mul_f32_e32 v55, v55, v193
	v_fma_f32 v55, v177, v55, v181
	v_sub_f32_e32 v56, v56, v192
	v_mul_f32_e32 v56, v56, v193
	v_fma_f32 v56, v178, v56, v182
	v_sub_f32_e32 v57, v57, v192
	v_mul_f32_e32 v57, v57, v193
	v_fma_f32 v57, v179, v57, v183
	global_store_dwordx4 v137, v[54:57], s[94:95] offset:128 nt
	ds_read_b128 v[176:179], v136 offset:256
	ds_read_b128 v[180:183], v136 offset:4352
	s_waitcnt lgkmcnt(2)
	v_sub_f32_e32 v50, v50, v192
	v_mul_f32_e32 v50, v50, v193
	v_fma_f32 v50, v184, v50, v188
	v_sub_f32_e32 v51, v51, v192
	v_mul_f32_e32 v51, v51, v193
	v_fma_f32 v51, v185, v51, v189
	v_sub_f32_e32 v52, v52, v192
	v_mul_f32_e32 v52, v52, v193
	v_fma_f32 v52, v186, v52, v190
	v_sub_f32_e32 v53, v53, v192
	v_mul_f32_e32 v53, v53, v193
	v_fma_f32 v53, v187, v53, v191
	global_store_dwordx4 v137, v[50:53], s[94:95] offset:192 nt
	ds_read_b128 v[184:187], v136 offset:320
	ds_read_b128 v[188:191], v136 offset:4416
	s_waitcnt lgkmcnt(2)
	v_sub_f32_e32 v46, v46, v192
	v_mul_f32_e32 v46, v46, v193
	v_fma_f32 v46, v176, v46, v180
	v_sub_f32_e32 v47, v47, v192
	v_mul_f32_e32 v47, v47, v193
	v_fma_f32 v47, v177, v47, v181
	v_sub_f32_e32 v48, v48, v192
	v_mul_f32_e32 v48, v48, v193
	v_fma_f32 v48, v178, v48, v182
	v_sub_f32_e32 v49, v49, v192
	v_mul_f32_e32 v49, v49, v193
	v_fma_f32 v49, v179, v49, v183
	global_store_dwordx4 v137, v[46:49], s[94:95] offset:256 nt
	ds_read_b128 v[176:179], v136 offset:384
	ds_read_b128 v[180:183], v136 offset:4480
	s_waitcnt lgkmcnt(2)
	v_sub_f32_e32 v42, v42, v192
	v_mul_f32_e32 v42, v42, v193
	v_fma_f32 v42, v184, v42, v188
	v_sub_f32_e32 v43, v43, v192
	v_mul_f32_e32 v43, v43, v193
	v_fma_f32 v43, v185, v43, v189
	v_sub_f32_e32 v44, v44, v192
	v_mul_f32_e32 v44, v44, v193
	v_fma_f32 v44, v186, v44, v190
	v_sub_f32_e32 v45, v45, v192
	v_mul_f32_e32 v45, v45, v193
	v_fma_f32 v45, v187, v45, v191
	global_store_dwordx4 v137, v[42:45], s[94:95] offset:320 nt
	ds_read_b128 v[184:187], v136 offset:448
	ds_read_b128 v[188:191], v136 offset:4544
	s_waitcnt lgkmcnt(2)
	v_sub_f32_e32 v38, v38, v192
	v_mul_f32_e32 v38, v38, v193
	v_fma_f32 v38, v176, v38, v180
	v_sub_f32_e32 v39, v39, v192
	v_mul_f32_e32 v39, v39, v193
	v_fma_f32 v39, v177, v39, v181
	v_sub_f32_e32 v40, v40, v192
	v_mul_f32_e32 v40, v40, v193
	v_fma_f32 v40, v178, v40, v182
	v_sub_f32_e32 v41, v41, v192
	v_mul_f32_e32 v41, v41, v193
	v_fma_f32 v41, v179, v41, v183
	global_store_dwordx4 v137, v[38:41], s[94:95] offset:384 nt
	s_waitcnt lgkmcnt(0)
	v_sub_f32_e32 v2, v2, v192
	v_mul_f32_e32 v2, v2, v193
	v_fma_f32 v2, v184, v2, v188
	v_sub_f32_e32 v3, v3, v192
	v_mul_f32_e32 v3, v3, v193
	v_fma_f32 v3, v185, v3, v189
	v_sub_f32_e32 v4, v4, v192
	v_mul_f32_e32 v4, v4, v193
	v_fma_f32 v4, v186, v4, v190
	v_sub_f32_e32 v5, v5, v192
	v_mul_f32_e32 v5, v5, v193
	v_fma_f32 v5, v187, v5, v191
	global_store_dwordx4 v137, v[2:5], s[94:95] offset:448 nt
